# write-through (sc1) on dwordx4 global stores: less dirty L2 for the barrier release fences
# baseline (speedup 1.0000x reference)
.Lwo1_go:
	v_ashrrev_i32_e32 v0, 6, v131
	v_add_u32_e32 v87, s14, v0
	v_lshlrev_b32_e32 v92, 12, v87
	v_mov_b32_e32 v93, 0
	v_mad_u32_u24 v91, v0, s33, v130
	v_lshl_add_u64 v[66:67], v[92:93], 0, v[88:89]
	global_load_dwordx4 v[140:143], v[66:67], off
	v_add_u32_e32 v92, 0x8000, v92
	v_lshl_add_u64 v[66:67], v[92:93], 0, v[88:89]
	global_load_dwordx4 v[144:147], v[66:67], off
	v_add_u32_e32 v92, 0x8000, v92
	v_lshl_add_u64 v[66:67], v[92:93], 0, v[88:89]
	global_load_dwordx4 v[148:151], v[66:67], off
	v_add_u32_e32 v92, 0x8000, v92
	v_lshl_add_u64 v[66:67], v[92:93], 0, v[88:89]
	global_load_dwordx4 v[152:155], v[66:67], off
	v_add_u32_e32 v92, 0x8000, v92
	v_lshl_add_u64 v[66:67], v[92:93], 0, v[88:89]
	global_load_dwordx4 v[156:159], v[66:67], off
	v_add_u32_e32 v92, 0x8000, v92
	v_lshl_add_u64 v[66:67], v[92:93], 0, v[88:89]
	global_load_dwordx4 v[160:163], v[66:67], off
	v_add_u32_e32 v92, 0x8000, v92
	v_lshl_add_u64 v[66:67], v[92:93], 0, v[88:89]
	global_load_dwordx4 v[164:167], v[66:67], off
	v_add_u32_e32 v92, 0x8000, v92
	v_lshl_add_u64 v[66:67], v[92:93], 0, v[88:89]
	global_load_dwordx4 v[172:175], v[66:67], off
	v_add_u32_e32 v92, 0x8000, v92
	v_lshl_add_u64 v[66:67], v[92:93], 0, v[88:89]
	global_load_dwordx4 v[176:179], v[66:67], off
	v_add_u32_e32 v92, 0x8000, v92
	v_lshl_add_u64 v[66:67], v[92:93], 0, v[88:89]
	global_load_dwordx4 v[180:183], v[66:67], off
	v_add_u32_e32 v92, 0x8000, v92
	v_lshl_add_u64 v[66:67], v[92:93], 0, v[88:89]
	global_load_dwordx4 v[184:187], v[66:67], off
	v_add_u32_e32 v92, 0x8000, v92
	v_lshl_add_u64 v[66:67], v[92:93], 0, v[88:89]
	global_load_dwordx4 v[188:191], v[66:67], off
	v_add_u32_e32 v92, 0x8000, v92
	v_lshl_add_u64 v[66:67], v[92:93], 0, v[88:89]
	global_load_dwordx4 v[192:195], v[66:67], off
	v_add_u32_e32 v92, 0x8000, v92
	v_lshl_add_u64 v[66:67], v[92:93], 0, v[88:89]
	global_load_dwordx4 v[196:199], v[66:67], off
	v_add_u32_e32 v92, 0x8000, v92
	v_lshl_add_u64 v[66:67], v[92:93], 0, v[88:89]
	global_load_dwordx4 v[220:223], v[66:67], off
	v_add_u32_e32 v92, 0x8000, v92
	v_lshl_add_u64 v[66:67], v[92:93], 0, v[88:89]
	global_load_dwordx4 v[224:227], v[66:67], off
	v_add_u32_e32 v92, 0x8000, v92
	v_add_u32_e32 v92, 0xfff80000, v92
	ds_read_b128 v[96:99], v91
	ds_read_b128 v[100:103], v91 offset:8320
	ds_read_b128 v[104:107], v91 offset:16640
	ds_read_b128 v[108:111], v91 offset:24960
	v_add_u32_e32 v91, 0x8200, v91
	s_waitcnt vmcnt(15) lgkmcnt(3)
	v_pk_add_f32 v[140:141], v[96:97], v[140:141]
	v_pk_add_f32 v[142:143], v[98:99], v[142:143]
	v_lshl_add_u64 v[70:71], v[92:93], 0, v[134:135]
	global_store_dwordx4 v[70:71], v[140:143], off sc1
	v_add_u32_e32 v92, 0x8000, v92
	s_waitcnt vmcnt(15) lgkmcnt(2)
	v_pk_add_f32 v[144:145], v[100:101], v[144:145]
	v_pk_add_f32 v[146:147], v[102:103], v[146:147]
	v_lshl_add_u64 v[70:71], v[92:93], 0, v[134:135]
	global_store_dwordx4 v[70:71], v[144:147], off sc1
	v_add_u32_e32 v92, 0x8000, v92
	s_waitcnt vmcnt(15) lgkmcnt(1)
	v_pk_add_f32 v[148:149], v[104:105], v[148:149]
	v_pk_add_f32 v[150:151], v[106:107], v[150:151]
	v_lshl_add_u64 v[70:71], v[92:93], 0, v[134:135]
	global_store_dwordx4 v[70:71], v[148:151], off sc1
	v_add_u32_e32 v92, 0x8000, v92
	s_waitcnt vmcnt(15) lgkmcnt(0)
	v_pk_add_f32 v[152:153], v[108:109], v[152:153]
	v_pk_add_f32 v[154:155], v[110:111], v[154:155]
	v_lshl_add_u64 v[70:71], v[92:93], 0, v[134:135]
	global_store_dwordx4 v[70:71], v[152:155], off sc1
	v_add_u32_e32 v92, 0x8000, v92
	ds_read_b128 v[96:99], v91
	ds_read_b128 v[100:103], v91 offset:8320
	ds_read_b128 v[104:107], v91 offset:16640
	ds_read_b128 v[108:111], v91 offset:24960
	v_add_u32_e32 v91, 0x8200, v91
	s_waitcnt vmcnt(15) lgkmcnt(3)
	v_pk_add_f32 v[156:157], v[96:97], v[156:157]
	v_pk_add_f32 v[158:159], v[98:99], v[158:159]
	v_lshl_add_u64 v[70:71], v[92:93], 0, v[134:135]
	global_store_dwordx4 v[70:71], v[156:159], off sc1
	v_add_u32_e32 v92, 0x8000, v92
	s_waitcnt vmcnt(15) lgkmcnt(2)
	v_pk_add_f32 v[160:161], v[100:101], v[160:161]
	v_pk_add_f32 v[162:163], v[102:103], v[162:163]
	v_lshl_add_u64 v[70:71], v[92:93], 0, v[134:135]
	global_store_dwordx4 v[70:71], v[160:163], off sc1
	v_add_u32_e32 v92, 0x8000, v92
	s_waitcnt vmcnt(15) lgkmcnt(1)
	v_pk_add_f32 v[164:165], v[104:105], v[164:165]
	v_pk_add_f32 v[166:167], v[106:107], v[166:167]
	v_lshl_add_u64 v[70:71], v[92:93], 0, v[134:135]
	global_store_dwordx4 v[70:71], v[164:167], off sc1
	v_add_u32_e32 v92, 0x8000, v92
	s_waitcnt vmcnt(15) lgkmcnt(0)
	v_pk_add_f32 v[172:173], v[108:109], v[172:173]
	v_pk_add_f32 v[174:175], v[110:111], v[174:175]
	v_lshl_add_u64 v[70:71], v[92:93], 0, v[134:135]
	global_store_dwordx4 v[70:71], v[172:175], off sc1
	v_add_u32_e32 v92, 0x8000, v92
	ds_read_b128 v[96:99], v91
	ds_read_b128 v[100:103], v91 offset:8320
	ds_read_b128 v[104:107], v91 offset:16640
	ds_read_b128 v[108:111], v91 offset:24960
	v_add_u32_e32 v91, 0x8200, v91
	s_waitcnt vmcnt(15) lgkmcnt(3)
	v_pk_add_f32 v[176:177], v[96:97], v[176:177]
	v_pk_add_f32 v[178:179], v[98:99], v[178:179]
	v_lshl_add_u64 v[70:71], v[92:93], 0, v[134:135]
	global_store_dwordx4 v[70:71], v[176:179], off sc1
	v_add_u32_e32 v92, 0x8000, v92
	s_waitcnt vmcnt(15) lgkmcnt(2)
	v_pk_add_f32 v[180:181], v[100:101], v[180:181]
	v_pk_add_f32 v[182:183], v[102:103], v[182:183]
	v_lshl_add_u64 v[70:71], v[92:93], 0, v[134:135]
	global_store_dwordx4 v[70:71], v[180:183], off sc1
	v_add_u32_e32 v92, 0x8000, v92
	s_waitcnt vmcnt(15) lgkmcnt(1)
	v_pk_add_f32 v[184:185], v[104:105], v[184:185]
	v_pk_add_f32 v[186:187], v[106:107], v[186:187]
	v_lshl_add_u64 v[70:71], v[92:93], 0, v[134:135]
	global_store_dwordx4 v[70:71], v[184:187], off sc1
	v_add_u32_e32 v92, 0x8000, v92
	s_waitcnt vmcnt(15) lgkmcnt(0)
	v_pk_add_f32 v[188:189], v[108:109], v[188:189]
	v_pk_add_f32 v[190:191], v[110:111], v[190:191]
	v_lshl_add_u64 v[70:71], v[92:93], 0, v[134:135]
	global_store_dwordx4 v[70:71], v[188:191], off sc1
	v_add_u32_e32 v92, 0x8000, v92
	ds_read_b128 v[96:99], v91
	ds_read_b128 v[100:103], v91 offset:8320
	ds_read_b128 v[104:107], v91 offset:16640
	ds_read_b128 v[108:111], v91 offset:24960
	v_add_u32_e32 v91, 0x8200, v91
	s_waitcnt vmcnt(15) lgkmcnt(3)
	v_pk_add_f32 v[192:193], v[96:97], v[192:193]
	v_pk_add_f32 v[194:195], v[98:99], v[194:195]
	v_lshl_add_u64 v[70:71], v[92:93], 0, v[134:135]
	global_store_dwordx4 v[70:71], v[192:195], off sc1
	v_add_u32_e32 v92, 0x8000, v92
	s_waitcnt vmcnt(15) lgkmcnt(2)
	v_pk_add_f32 v[196:197], v[100:101], v[196:197]
	v_pk_add_f32 v[198:199], v[102:103], v[198:199]
	v_lshl_add_u64 v[70:71], v[92:93], 0, v[134:135]
	global_store_dwordx4 v[70:71], v[196:199], off sc1
	v_add_u32_e32 v92, 0x8000, v92
	s_waitcnt vmcnt(15) lgkmcnt(1)
	v_pk_add_f32 v[220:221], v[104:105], v[220:221]
	v_pk_add_f32 v[222:223], v[106:107], v[222:223]
	v_lshl_add_u64 v[70:71], v[92:93], 0, v[134:135]
	global_store_dwordx4 v[70:71], v[220:223], off sc1
	v_add_u32_e32 v92, 0x8000, v92
	s_waitcnt vmcnt(15) lgkmcnt(0)
	v_pk_add_f32 v[224:225], v[108:109], v[224:225]
	v_pk_add_f32 v[226:227], v[110:111], v[226:227]
	v_lshl_add_u64 v[70:71], v[92:93], 0, v[134:135]
	global_store_dwordx4 v[70:71], v[224:227], off sc1
	v_add_u32_e32 v92, 0x8000, v92

.Lwo2_go:
	v_ashrrev_i32_e32 v0, 6, v131
	v_add_u32_e32 v87, s14, v0
	v_lshlrev_b32_e32 v92, 12, v87
	v_mov_b32_e32 v93, 0
	v_mad_u32_u24 v91, v0, s33, v130
	v_lshl_add_u64 v[66:67], v[92:93], 0, v[88:89]
	global_load_dwordx4 v[140:143], v[66:67], off
	v_add_u32_e32 v92, 0x8000, v92
	v_lshl_add_u64 v[66:67], v[92:93], 0, v[88:89]
	global_load_dwordx4 v[144:147], v[66:67], off
	v_add_u32_e32 v92, 0x8000, v92
	v_lshl_add_u64 v[66:67], v[92:93], 0, v[88:89]
	global_load_dwordx4 v[148:151], v[66:67], off
	v_add_u32_e32 v92, 0x8000, v92
	v_lshl_add_u64 v[66:67], v[92:93], 0, v[88:89]
	global_load_dwordx4 v[152:155], v[66:67], off
	v_add_u32_e32 v92, 0x8000, v92
	v_lshl_add_u64 v[66:67], v[92:93], 0, v[88:89]
	global_load_dwordx4 v[156:159], v[66:67], off
	v_add_u32_e32 v92, 0x8000, v92
	v_lshl_add_u64 v[66:67], v[92:93], 0, v[88:89]
	global_load_dwordx4 v[160:163], v[66:67], off
	v_add_u32_e32 v92, 0x8000, v92
	v_lshl_add_u64 v[66:67], v[92:93], 0, v[88:89]
	global_load_dwordx4 v[164:167], v[66:67], off
	v_add_u32_e32 v92, 0x8000, v92
	v_lshl_add_u64 v[66:67], v[92:93], 0, v[88:89]
	global_load_dwordx4 v[172:175], v[66:67], off
	v_add_u32_e32 v92, 0x8000, v92
	v_lshl_add_u64 v[66:67], v[92:93], 0, v[88:89]
	global_load_dwordx4 v[176:179], v[66:67], off
	v_add_u32_e32 v92, 0x8000, v92
	v_lshl_add_u64 v[66:67], v[92:93], 0, v[88:89]
	global_load_dwordx4 v[180:183], v[66:67], off
	v_add_u32_e32 v92, 0x8000, v92
	v_lshl_add_u64 v[66:67], v[92:93], 0, v[88:89]
	global_load_dwordx4 v[184:187], v[66:67], off
	v_add_u32_e32 v92, 0x8000, v92
	v_lshl_add_u64 v[66:67], v[92:93], 0, v[88:89]
	global_load_dwordx4 v[188:191], v[66:67], off
	v_add_u32_e32 v92, 0x8000, v92
	v_lshl_add_u64 v[66:67], v[92:93], 0, v[88:89]
	global_load_dwordx4 v[192:195], v[66:67], off
	v_add_u32_e32 v92, 0x8000, v92
	v_lshl_add_u64 v[66:67], v[92:93], 0, v[88:89]
	global_load_dwordx4 v[196:199], v[66:67], off
	v_add_u32_e32 v92, 0x8000, v92
	v_lshl_add_u64 v[66:67], v[92:93], 0, v[88:89]
	global_load_dwordx4 v[220:223], v[66:67], off
	v_add_u32_e32 v92, 0x8000, v92
	v_lshl_add_u64 v[66:67], v[92:93], 0, v[88:89]
	global_load_dwordx4 v[224:227], v[66:67], off
	v_add_u32_e32 v92, 0x8000, v92
	v_add_u32_e32 v92, 0xfff80000, v92
	ds_read_b128 v[96:99], v91
	ds_read_b128 v[100:103], v91 offset:8320
	ds_read_b128 v[104:107], v91 offset:16640
	ds_read_b128 v[108:111], v91 offset:24960
	v_add_u32_e32 v91, 0x8200, v91
	s_waitcnt vmcnt(15) lgkmcnt(3)
	v_pk_add_f32 v[140:141], v[96:97], v[140:141]
	v_pk_add_f32 v[142:143], v[98:99], v[142:143]
	v_lshl_add_u64 v[70:71], v[92:93], 0, v[134:135]
	global_store_dwordx4 v[70:71], v[140:143], off sc1
	v_add_u32_e32 v92, 0x8000, v92
	s_waitcnt vmcnt(15) lgkmcnt(2)
	v_pk_add_f32 v[144:145], v[100:101], v[144:145]
	v_pk_add_f32 v[146:147], v[102:103], v[146:147]
	v_lshl_add_u64 v[70:71], v[92:93], 0, v[134:135]
	global_store_dwordx4 v[70:71], v[144:147], off sc1
	v_add_u32_e32 v92, 0x8000, v92
	s_waitcnt vmcnt(15) lgkmcnt(1)
	v_pk_add_f32 v[148:149], v[104:105], v[148:149]
	v_pk_add_f32 v[150:151], v[106:107], v[150:151]
	v_lshl_add_u64 v[70:71], v[92:93], 0, v[134:135]
	global_store_dwordx4 v[70:71], v[148:151], off sc1
	v_add_u32_e32 v92, 0x8000, v92
	s_waitcnt vmcnt(15) lgkmcnt(0)
	v_pk_add_f32 v[152:153], v[108:109], v[152:153]
	v_pk_add_f32 v[154:155], v[110:111], v[154:155]
	v_lshl_add_u64 v[70:71], v[92:93], 0, v[134:135]
	global_store_dwordx4 v[70:71], v[152:155], off sc1
	v_add_u32_e32 v92, 0x8000, v92
	ds_read_b128 v[96:99], v91
	ds_read_b128 v[100:103], v91 offset:8320
	ds_read_b128 v[104:107], v91 offset:16640
	ds_read_b128 v[108:111], v91 offset:24960
	v_add_u32_e32 v91, 0x8200, v91
	s_waitcnt vmcnt(15) lgkmcnt(3)
	v_pk_add_f32 v[156:157], v[96:97], v[156:157]
	v_pk_add_f32 v[158:159], v[98:99], v[158:159]
	v_lshl_add_u64 v[70:71], v[92:93], 0, v[134:135]
	global_store_dwordx4 v[70:71], v[156:159], off sc1
	v_add_u32_e32 v92, 0x8000, v92
	s_waitcnt vmcnt(15) lgkmcnt(2)
	v_pk_add_f32 v[160:161], v[100:101], v[160:161]
	v_pk_add_f32 v[162:163], v[102:103], v[162:163]
	v_lshl_add_u64 v[70:71], v[92:93], 0, v[134:135]
	global_store_dwordx4 v[70:71], v[160:163], off sc1
	v_add_u32_e32 v92, 0x8000, v92
	s_waitcnt vmcnt(15) lgkmcnt(1)
	v_pk_add_f32 v[164:165], v[104:105], v[164:165]
	v_pk_add_f32 v[166:167], v[106:107], v[166:167]
	v_lshl_add_u64 v[70:71], v[92:93], 0, v[134:135]
	global_store_dwordx4 v[70:71], v[164:167], off sc1
	v_add_u32_e32 v92, 0x8000, v92
	s_waitcnt vmcnt(15) lgkmcnt(0)
	v_pk_add_f32 v[172:173], v[108:109], v[172:173]
	v_pk_add_f32 v[174:175], v[110:111], v[174:175]
	v_lshl_add_u64 v[70:71], v[92:93], 0, v[134:135]
	global_store_dwordx4 v[70:71], v[172:175], off sc1
	v_add_u32_e32 v92, 0x8000, v92
	ds_read_b128 v[96:99], v91
	ds_read_b128 v[100:103], v91 offset:8320
	ds_read_b128 v[104:107], v91 offset:16640
	ds_read_b128 v[108:111], v91 offset:24960
	v_add_u32_e32 v91, 0x8200, v91
	s_waitcnt vmcnt(15) lgkmcnt(3)
	v_pk_add_f32 v[176:177], v[96:97], v[176:177]
	v_pk_add_f32 v[178:179], v[98:99], v[178:179]
	v_lshl_add_u64 v[70:71], v[92:93], 0, v[134:135]
	global_store_dwordx4 v[70:71], v[176:179], off sc1
	v_add_u32_e32 v92, 0x8000, v92
	s_waitcnt vmcnt(15) lgkmcnt(2)
	v_pk_add_f32 v[180:181], v[100:101], v[180:181]
	v_pk_add_f32 v[182:183], v[102:103], v[182:183]
	v_lshl_add_u64 v[70:71], v[92:93], 0, v[134:135]
	global_store_dwordx4 v[70:71], v[180:183], off sc1
	v_add_u32_e32 v92, 0x8000, v92
	s_waitcnt vmcnt(15) lgkmcnt(1)
	v_pk_add_f32 v[184:185], v[104:105], v[184:185]
	v_pk_add_f32 v[186:187], v[106:107], v[186:187]
	v_lshl_add_u64 v[70:71], v[92:93], 0, v[134:135]
	global_store_dwordx4 v[70:71], v[184:187], off sc1
	v_add_u32_e32 v92, 0x8000, v92
	s_waitcnt vmcnt(15) lgkmcnt(0)
	v_pk_add_f32 v[188:189], v[108:109], v[188:189]
	v_pk_add_f32 v[190:191], v[110:111], v[190:191]
	v_lshl_add_u64 v[70:71], v[92:93], 0, v[134:135]
	global_store_dwordx4 v[70:71], v[188:191], off sc1
	v_add_u32_e32 v92, 0x8000, v92
	ds_read_b128 v[96:99], v91
	ds_read_b128 v[100:103], v91 offset:8320
	ds_read_b128 v[104:107], v91 offset:16640
	ds_read_b128 v[108:111], v91 offset:24960
	v_add_u32_e32 v91, 0x8200, v91
	s_waitcnt vmcnt(15) lgkmcnt(3)
	v_pk_add_f32 v[192:193], v[96:97], v[192:193]
	v_pk_add_f32 v[194:195], v[98:99], v[194:195]
	v_lshl_add_u64 v[70:71], v[92:93], 0, v[134:135]
	global_store_dwordx4 v[70:71], v[192:195], off sc1
	v_add_u32_e32 v92, 0x8000, v92
	s_waitcnt vmcnt(15) lgkmcnt(2)
	v_pk_add_f32 v[196:197], v[100:101], v[196:197]
	v_pk_add_f32 v[198:199], v[102:103], v[198:199]
	v_lshl_add_u64 v[70:71], v[92:93], 0, v[134:135]
	global_store_dwordx4 v[70:71], v[196:199], off sc1
	v_add_u32_e32 v92, 0x8000, v92
	s_waitcnt vmcnt(15) lgkmcnt(1)
	v_pk_add_f32 v[220:221], v[104:105], v[220:221]
	v_pk_add_f32 v[222:223], v[106:107], v[222:223]
	v_lshl_add_u64 v[70:71], v[92:93], 0, v[134:135]
	global_store_dwordx4 v[70:71], v[220:223], off sc1
	v_add_u32_e32 v92, 0x8000, v92
	s_waitcnt vmcnt(15) lgkmcnt(0)
	v_pk_add_f32 v[224:225], v[108:109], v[224:225]
	v_pk_add_f32 v[226:227], v[110:111], v[226:227]
	v_lshl_add_u64 v[70:71], v[92:93], 0, v[134:135]
	global_store_dwordx4 v[70:71], v[224:227], off sc1
	v_add_u32_e32 v92, 0x8000, v92
	s_branch .LBB0_30

.LBB0_374:
	s_or_b64 exec, exec, s[26:27]
	s_waitcnt vmcnt(1) lgkmcnt(0)
	v_add_f32_e32 v76, v8, v76
	v_mul_f32_e32 v76, 0xbfb8aa3b, v76
	v_exp_f32_e32 v76, v76
	v_add_f32_e32 v77, v9, v77
	v_mul_f32_e32 v77, 0xbfb8aa3b, v77
	v_exp_f32_e32 v77, v77
	v_add_f32_e32 v76, 1.0, v76
	v_div_scale_f32 v100, s[4:5], v76, v76, 1.0
	v_rcp_f32_e32 v101, v100
	v_div_scale_f32 v105, vcc, 1.0, v76, 1.0
	v_add_f32_e32 v77, 1.0, v77
	v_fma_f32 v106, -v100, v101, 1.0
	v_fmac_f32_e32 v101, v106, v101
	v_mul_f32_e32 v106, v105, v101
	v_fma_f32 v107, -v100, v106, v105
	v_fmac_f32_e32 v106, v107, v101
	v_fma_f32 v100, -v100, v106, v105
	v_div_fmas_f32 v100, v100, v101, v106
	v_div_fixup_f32 v76, v100, v76, 1.0
	v_div_scale_f32 v100, s[4:5], v77, v77, 1.0
	v_rcp_f32_e32 v101, v100
	v_add_f32_e32 v75, v7, v75
	v_mul_f32_e32 v75, 0xbfb8aa3b, v75
	v_mul_f32_e32 v76, v76, v97
	v_fma_f32 v97, -v100, v101, 1.0
	v_exp_f32_e32 v75, v75
	s_waitcnt vmcnt(0)
	v_lshlrev_b32_e32 v105, 16, v83
	v_fmac_f32_e32 v101, v97, v101
	v_div_scale_f32 v97, vcc, 1.0, v77, 1.0
	v_mul_f32_e32 v76, v76, v105
	v_mul_f32_e32 v105, v97, v101
	v_fma_f32 v106, -v100, v105, v97
	v_fmac_f32_e32 v105, v106, v101
	v_add_f32_e32 v75, 1.0, v75
	v_fma_f32 v97, -v100, v105, v97
	v_div_scale_f32 v100, s[4:5], v75, v75, 1.0
	v_div_fmas_f32 v97, v97, v101, v105
	v_rcp_f32_e32 v101, v100
	v_div_fixup_f32 v77, v97, v77, 1.0
	v_mul_f32_e32 v97, 0x3fb8aa3b, v99
	v_exp_f32_e32 v109, v97
	v_fma_f32 v97, -v100, v101, 1.0
	v_fmac_f32_e32 v101, v97, v101
	v_div_scale_f32 v97, vcc, 1.0, v75, 1.0
	v_add_f32_e32 v74, v6, v74
	v_mul_f32_e32 v99, v97, v101
	v_mul_f32_e32 v74, 0xbfb8aa3b, v74
	v_fma_f32 v105, -v100, v99, v97
	v_exp_f32_e32 v74, v74
	v_fmac_f32_e32 v99, v105, v101
	v_fma_f32 v97, -v100, v99, v97
	v_div_fmas_f32 v97, v97, v101, v99
	v_div_fixup_f32 v75, v97, v75, 1.0
	v_add_f32_e32 v74, 1.0, v74
	v_and_b32_e32 v97, 0xffff0000, v82
	v_mul_f32_e32 v75, v75, v96
	v_div_scale_f32 v96, s[4:5], v74, v74, 1.0
	v_mul_f32_e32 v75, v75, v97
	v_rcp_f32_e32 v97, v96
	v_mul_f32_e32 v80, 0x3fb8aa3b, v80
	v_exp_f32_e32 v108, v80
	v_lshlrev_b32_e32 v80, 16, v82
	v_fma_f32 v82, -v96, v97, 1.0
	v_fmac_f32_e32 v97, v82, v97
	v_div_scale_f32 v82, vcc, 1.0, v74, 1.0
	v_mul_f32_e32 v99, v82, v97
	v_fma_f32 v100, -v96, v99, v82
	v_fmac_f32_e32 v99, v100, v97
	v_fma_f32 v82, -v96, v99, v82
	v_mul_f32_e32 v79, 0x3fb8aa3b, v79
	v_mul_f32_e32 v78, 0x3fb8aa3b, v78
	v_div_fmas_f32 v82, v82, v97, v99
	v_exp_f32_e32 v107, v79
	v_exp_f32_e32 v106, v78
	v_div_fixup_f32 v74, v82, v74, 1.0
	v_and_b32_e32 v79, 0xffff0000, v83
	v_mul_f32_e32 v77, v77, v81
	v_mul_f32_e32 v74, v74, v95
	v_mul_f32_e32 v77, v77, v79
	v_lshlrev_b64 v[78:79], 2, v[84:85]
	v_mul_f32_e32 v74, v74, v80
	v_lshl_add_u64 v[80:81], v[142:143], 0, v[78:79]
	v_lshl_add_u64 v[78:79], v[144:145], 0, v[78:79]
	global_store_dwordx4 v[80:81], v[106:109], off sc1
	global_store_dwordx4 v[78:79], v[74:77], off sc1

.LBB0_401:
	s_or_b64 exec, exec, s[26:27]
	s_waitcnt vmcnt(1) lgkmcnt(0)
	v_add_f32_e32 v76, v8, v76
	v_mul_f32_e32 v76, 0xbfb8aa3b, v76
	v_exp_f32_e32 v76, v76
	v_add_f32_e32 v77, v9, v77
	v_mul_f32_e32 v77, 0xbfb8aa3b, v77
	v_exp_f32_e32 v77, v77
	v_add_f32_e32 v76, 1.0, v76
	v_div_scale_f32 v101, s[4:5], v76, v76, 1.0
	v_rcp_f32_e32 v105, v101
	v_div_scale_f32 v106, vcc, 1.0, v76, 1.0
	v_add_f32_e32 v77, 1.0, v77
	v_fma_f32 v107, -v101, v105, 1.0
	v_fmac_f32_e32 v105, v107, v105
	v_mul_f32_e32 v107, v106, v105
	v_fma_f32 v108, -v101, v107, v106
	v_fmac_f32_e32 v107, v108, v105
	v_fma_f32 v101, -v101, v107, v106
	v_div_fmas_f32 v101, v101, v105, v107
	v_div_fixup_f32 v76, v101, v76, 1.0
	v_div_scale_f32 v101, s[4:5], v77, v77, 1.0
	v_rcp_f32_e32 v105, v101
	v_add_f32_e32 v75, v7, v75
	v_mul_f32_e32 v75, 0xbfb8aa3b, v75
	v_mul_f32_e32 v76, v76, v99
	v_fma_f32 v99, -v101, v105, 1.0
	v_exp_f32_e32 v75, v75
	s_waitcnt vmcnt(0)
	v_lshlrev_b32_e32 v106, 16, v83
	v_fmac_f32_e32 v105, v99, v105
	v_div_scale_f32 v99, vcc, 1.0, v77, 1.0
	v_mul_f32_e32 v76, v76, v106
	v_mul_f32_e32 v106, v99, v105
	v_fma_f32 v107, -v101, v106, v99
	v_fmac_f32_e32 v106, v107, v105
	v_add_f32_e32 v75, 1.0, v75
	v_fma_f32 v99, -v101, v106, v99
	v_div_scale_f32 v101, s[4:5], v75, v75, 1.0
	v_div_fmas_f32 v99, v99, v105, v106
	v_rcp_f32_e32 v105, v101
	v_div_fixup_f32 v77, v99, v77, 1.0
	v_mul_f32_e32 v99, 0x3fb8aa3b, v100
	v_exp_f32_e32 v109, v99
	v_fma_f32 v99, -v101, v105, 1.0
	v_fmac_f32_e32 v105, v99, v105
	v_div_scale_f32 v99, vcc, 1.0, v75, 1.0
	v_add_f32_e32 v74, v6, v74
	v_mul_f32_e32 v100, v99, v105
	v_mul_f32_e32 v74, 0xbfb8aa3b, v74
	v_fma_f32 v106, -v101, v100, v99
	v_exp_f32_e32 v74, v74
	v_fmac_f32_e32 v100, v106, v105
	v_fma_f32 v99, -v101, v100, v99
	v_div_fmas_f32 v99, v99, v105, v100
	v_div_fixup_f32 v75, v99, v75, 1.0
	v_add_f32_e32 v74, 1.0, v74
	v_and_b32_e32 v99, 0xffff0000, v82
	v_mul_f32_e32 v75, v75, v97
	v_div_scale_f32 v97, s[4:5], v74, v74, 1.0
	v_mul_f32_e32 v75, v75, v99
	v_rcp_f32_e32 v99, v97
	v_mul_f32_e32 v80, 0x3fb8aa3b, v80
	v_exp_f32_e32 v108, v80
	v_lshlrev_b32_e32 v80, 16, v82
	v_fma_f32 v82, -v97, v99, 1.0
	v_fmac_f32_e32 v99, v82, v99
	v_div_scale_f32 v82, vcc, 1.0, v74, 1.0
	v_mul_f32_e32 v100, v82, v99
	v_fma_f32 v101, -v97, v100, v82
	v_fmac_f32_e32 v100, v101, v99
	v_fma_f32 v82, -v97, v100, v82
	v_mul_f32_e32 v79, 0x3fb8aa3b, v79
	v_mul_f32_e32 v78, 0x3fb8aa3b, v78
	v_div_fmas_f32 v82, v82, v99, v100
	v_exp_f32_e32 v107, v79
	v_exp_f32_e32 v106, v78
	v_div_fixup_f32 v74, v82, v74, 1.0
	v_and_b32_e32 v79, 0xffff0000, v83
	v_mul_f32_e32 v77, v77, v81
	v_mul_f32_e32 v74, v74, v96
	v_mul_f32_e32 v77, v77, v79
	v_lshlrev_b64 v[78:79], 2, v[84:85]
	v_mul_f32_e32 v74, v74, v80
	v_lshl_add_u64 v[80:81], v[142:143], 0, v[78:79]
	v_lshl_add_u64 v[78:79], v[144:145], 0, v[78:79]
	global_store_dwordx4 v[80:81], v[106:109], off sc1
	global_store_dwordx4 v[78:79], v[74:77], off sc1

.LBB0_428:
	s_or_b64 exec, exec, s[26:27]
	s_waitcnt vmcnt(1) lgkmcnt(0)
	v_add_f32_e32 v12, v8, v12
	v_mul_f32_e32 v12, 0xbfb8aa3b, v12
	v_exp_f32_e32 v12, v12
	v_add_f32_e32 v13, v9, v13
	v_mul_f32_e32 v13, 0xbfb8aa3b, v13
	v_exp_f32_e32 v13, v13
	v_add_f32_e32 v12, 1.0, v12
	v_div_scale_f32 v25, s[4:5], v12, v12, 1.0
	v_rcp_f32_e32 v26, v25
	v_div_scale_f32 v27, vcc, 1.0, v12, 1.0
	v_add_f32_e32 v13, 1.0, v13
	v_fma_f32 v28, -v25, v26, 1.0
	v_fmac_f32_e32 v26, v28, v26
	v_mul_f32_e32 v28, v27, v26
	v_fma_f32 v29, -v25, v28, v27
	v_fmac_f32_e32 v28, v29, v26
	v_fma_f32 v25, -v25, v28, v27
	v_div_fmas_f32 v25, v25, v26, v28
	v_div_fixup_f32 v12, v25, v12, 1.0
	v_div_scale_f32 v25, s[4:5], v13, v13, 1.0
	v_rcp_f32_e32 v26, v25
	v_add_f32_e32 v11, v7, v11
	v_mul_f32_e32 v12, v12, v23
	v_mul_f32_e32 v11, 0xbfb8aa3b, v11
	v_fma_f32 v23, -v25, v26, 1.0
	s_waitcnt vmcnt(0)
	v_lshlrev_b32_e32 v27, 16, v19
	v_fmac_f32_e32 v26, v23, v26
	v_div_scale_f32 v23, vcc, 1.0, v13, 1.0
	v_exp_f32_e32 v11, v11
	v_mul_f32_e32 v12, v12, v27
	v_mul_f32_e32 v27, v23, v26
	v_fma_f32 v28, -v25, v27, v23
	v_fmac_f32_e32 v27, v28, v26
	v_fma_f32 v23, -v25, v27, v23
	v_add_f32_e32 v11, 1.0, v11
	v_div_fmas_f32 v23, v23, v26, v27
	v_div_scale_f32 v26, s[4:5], v11, v11, 1.0
	v_rcp_f32_e32 v27, v26
	v_div_fixup_f32 v13, v23, v13, 1.0
	v_mul_f32_e32 v23, 0x3fb8aa3b, v24
	v_exp_f32_e32 v25, v23
	v_fma_f32 v23, -v26, v27, 1.0
	v_fmac_f32_e32 v27, v23, v27
	v_div_scale_f32 v23, vcc, 1.0, v11, 1.0
	v_add_f32_e32 v10, v6, v10
	v_mul_f32_e32 v24, v23, v27
	v_mul_f32_e32 v10, 0xbfb8aa3b, v10
	v_fma_f32 v28, -v26, v24, v23
	v_exp_f32_e32 v10, v10
	v_fmac_f32_e32 v24, v28, v27
	v_fma_f32 v23, -v26, v24, v23
	v_div_fmas_f32 v23, v23, v27, v24
	v_div_fixup_f32 v11, v23, v11, 1.0
	v_add_f32_e32 v10, 1.0, v10
	v_and_b32_e32 v23, 0xffff0000, v18
	v_mul_f32_e32 v11, v11, v22
	v_div_scale_f32 v22, s[4:5], v10, v10, 1.0
	v_mul_f32_e32 v11, v11, v23
	v_rcp_f32_e32 v23, v22
	v_mul_f32_e32 v16, 0x3fb8aa3b, v16
	v_exp_f32_e32 v24, v16
	v_lshlrev_b32_e32 v16, 16, v18
	v_fma_f32 v18, -v22, v23, 1.0
	v_fmac_f32_e32 v23, v18, v23
	v_div_scale_f32 v18, vcc, 1.0, v10, 1.0
	v_mul_f32_e32 v26, v18, v23
	v_fma_f32 v27, -v22, v26, v18
	v_fmac_f32_e32 v26, v27, v23
	v_fma_f32 v18, -v22, v26, v18
	v_div_fmas_f32 v18, v18, v23, v26
	v_div_fixup_f32 v10, v18, v10, 1.0
	v_mul_f32_e32 v10, v10, v14
	v_mul_f32_e32 v14, 0x3fb8aa3b, v15
	v_mul_f32_e32 v0, 0x3fb8aa3b, v0
	v_exp_f32_e32 v23, v14
	v_exp_f32_e32 v22, v0
	v_and_b32_e32 v14, 0xffff0000, v19
	v_mul_f32_e32 v0, v13, v17
	v_mul_f32_e32 v13, v0, v14
	v_lshlrev_b64 v[14:15], 2, v[20:21]
	v_mul_f32_e32 v10, v10, v16
	v_lshl_add_u64 v[16:17], v[142:143], 0, v[14:15]
	v_lshl_add_u64 v[14:15], v[144:145], 0, v[14:15]
	global_store_dwordx4 v[16:17], v[22:25], off sc1
	global_store_dwordx4 v[14:15], v[10:13], off sc1

.LBB0_455:
	s_or_b64 exec, exec, s[26:27]
	s_waitcnt vmcnt(1) lgkmcnt(0)
	v_add_f32_e32 v12, v8, v12
	v_mul_f32_e32 v12, 0xbfb8aa3b, v12
	v_exp_f32_e32 v12, v12
	v_add_f32_e32 v13, v9, v13
	v_mul_f32_e32 v13, 0xbfb8aa3b, v13
	v_exp_f32_e32 v13, v13
	v_add_f32_e32 v12, 1.0, v12
	v_div_scale_f32 v26, s[4:5], v12, v12, 1.0
	v_rcp_f32_e32 v27, v26
	v_div_scale_f32 v28, vcc, 1.0, v12, 1.0
	v_add_f32_e32 v13, 1.0, v13
	v_fma_f32 v29, -v26, v27, 1.0
	v_fmac_f32_e32 v27, v29, v27
	v_mul_f32_e32 v29, v28, v27
	v_fma_f32 v30, -v26, v29, v28
	v_fmac_f32_e32 v29, v30, v27
	v_fma_f32 v26, -v26, v29, v28
	v_div_fmas_f32 v26, v26, v27, v29
	v_div_fixup_f32 v12, v26, v12, 1.0
	v_div_scale_f32 v26, s[4:5], v13, v13, 1.0
	v_rcp_f32_e32 v27, v26
	v_add_f32_e32 v11, v7, v11
	v_mul_f32_e32 v11, 0xbfb8aa3b, v11
	v_mul_f32_e32 v12, v12, v24
	v_fma_f32 v24, -v26, v27, 1.0
	v_exp_f32_e32 v11, v11
	s_waitcnt vmcnt(0)
	v_lshlrev_b32_e32 v28, 16, v19
	v_fmac_f32_e32 v27, v24, v27
	v_div_scale_f32 v24, vcc, 1.0, v13, 1.0
	v_mul_f32_e32 v12, v12, v28
	v_mul_f32_e32 v28, v24, v27
	v_fma_f32 v29, -v26, v28, v24
	v_fmac_f32_e32 v28, v29, v27
	v_add_f32_e32 v11, 1.0, v11
	v_fma_f32 v24, -v26, v28, v24
	v_div_scale_f32 v26, s[4:5], v11, v11, 1.0
	v_div_fmas_f32 v24, v24, v27, v28
	v_rcp_f32_e32 v27, v26
	v_div_fixup_f32 v13, v24, v13, 1.0
	v_mul_f32_e32 v24, 0x3fb8aa3b, v25
	v_exp_f32_e32 v25, v24
	v_fma_f32 v24, -v26, v27, 1.0
	v_fmac_f32_e32 v27, v24, v27
	v_div_scale_f32 v24, vcc, 1.0, v11, 1.0
	v_add_f32_e32 v10, v6, v10
	v_mul_f32_e32 v28, v24, v27
	v_mul_f32_e32 v10, 0xbfb8aa3b, v10
	v_fma_f32 v29, -v26, v28, v24
	v_exp_f32_e32 v10, v10
	v_fmac_f32_e32 v28, v29, v27
	v_fma_f32 v24, -v26, v28, v24
	v_div_fmas_f32 v24, v24, v27, v28
	v_div_fixup_f32 v11, v24, v11, 1.0
	v_add_f32_e32 v10, 1.0, v10
	v_mul_f32_e32 v11, v11, v23
	v_div_scale_f32 v23, s[4:5], v10, v10, 1.0
	v_rcp_f32_e32 v26, v23
	v_and_b32_e32 v24, 0xffff0000, v18
	v_mul_f32_e32 v16, 0x3fb8aa3b, v16
	v_mul_f32_e32 v11, v11, v24
	v_exp_f32_e32 v24, v16
	v_lshlrev_b32_e32 v16, 16, v18
	v_fma_f32 v18, -v23, v26, 1.0
	v_fmac_f32_e32 v26, v18, v26
	v_div_scale_f32 v18, vcc, 1.0, v10, 1.0
	v_mul_f32_e32 v27, v18, v26
	v_fma_f32 v28, -v23, v27, v18
	v_fmac_f32_e32 v27, v28, v26
	v_fma_f32 v18, -v23, v27, v18
	v_div_fmas_f32 v18, v18, v26, v27
	v_div_fixup_f32 v10, v18, v10, 1.0
	v_mul_f32_e32 v15, 0x3fb8aa3b, v15
	v_mul_f32_e32 v14, 0x3fb8aa3b, v14
	v_mul_f32_e32 v10, v10, v22
	v_exp_f32_e32 v23, v15
	v_exp_f32_e32 v22, v14
	v_and_b32_e32 v15, 0xffff0000, v19
	v_mul_f32_e32 v13, v13, v17
	v_mul_f32_e32 v13, v13, v15
	v_lshlrev_b64 v[14:15], 2, v[20:21]
	v_mul_f32_e32 v10, v10, v16
	v_lshl_add_u64 v[16:17], v[142:143], 0, v[14:15]
	v_lshl_add_u64 v[14:15], v[144:145], 0, v[14:15]
	global_store_dwordx4 v[16:17], v[22:25], off sc1
	global_store_dwordx4 v[14:15], v[10:13], off sc1

.LBB0_569:
	s_or_b64 exec, exec, s[8:9]
	v_lshlrev_b32_e32 v0, 1, v98
	v_lshl_add_u64 v[54:55], v[28:29], 0, v[0:1]
	s_movk_i32 s0, 0x1000
	s_waitcnt vmcnt(1)
	v_lshlrev_b32_e32 v36, 16, v2
	v_and_b32_e32 v37, 0xffff0000, v2
	v_add_co_u32_e32 v2, vcc, s0, v54
	v_lshlrev_b32_e32 v34, 16, v3
	v_and_b32_e32 v35, 0xffff0000, v3
	v_addc_co_u32_e32 v3, vcc, 0, v55, vcc
	v_lshlrev_b32_e32 v52, 16, v10
	v_and_b32_e32 v53, 0xffff0000, v10
	v_lshlrev_b32_e32 v50, 16, v11
	v_and_b32_e32 v51, 0xffff0000, v11
	v_lshlrev_b32_e32 v48, 16, v12
	v_and_b32_e32 v49, 0xffff0000, v12
	s_waitcnt vmcnt(0)
	v_lshlrev_b32_e32 v46, 16, v13
	v_and_b32_e32 v47, 0xffff0000, v13
	global_load_dwordx4 v[10:13], v[2:3], off offset:2048
	s_lshl_b64 s[6:7], s[48:49], 2
	s_add_u32 s8, s12, s6
	s_addc_u32 s9, s13, s7
	v_lshlrev_b32_e32 v0, 2, v98
	v_lshl_add_u64 v[58:59], s[8:9], 0, v[0:1]
	s_mov_b64 s[10:11], 0x1000
	v_lshl_add_u64 v[74:75], v[58:59], 0, s[10:11]
	s_mov_b64 s[10:11], 0x1800
	s_lshl_b64 s[6:7], s[50:51], 2
	v_lshl_add_u64 v[82:83], v[58:59], 0, s[10:11]
	v_add_co_u32_e32 v58, vcc, s0, v58
	s_add_u32 s6, s14, s6
	s_nop 0
	v_addc_co_u32_e32 v59, vcc, 0, v59, vcc
	s_addc_u32 s7, s15, s7
	v_lshlrev_b32_e32 v30, 16, v4
	v_and_b32_e32 v31, 0xffff0000, v4
	v_lshlrev_b32_e32 v32, 16, v5
	v_and_b32_e32 v33, 0xffff0000, v5
	v_lshlrev_b32_e32 v44, 16, v6
	v_and_b32_e32 v45, 0xffff0000, v6
	v_lshlrev_b32_e32 v42, 16, v7
	v_and_b32_e32 v43, 0xffff0000, v7
	v_lshlrev_b32_e32 v40, 16, v8
	v_and_b32_e32 v41, 0xffff0000, v8
	v_lshlrev_b32_e32 v38, 16, v9
	v_and_b32_e32 v39, 0xffff0000, v9
	v_lshlrev_b64 v[28:29], 10, v[18:19]
	v_cndmask_b32_e64 v15, 13, v207, s[4:5]
	v_lshl_add_u64 v[28:29], v[100:101], 0, v[28:29]
	v_cmp_ge_u32_e32 vcc, v20, v15
	s_waitcnt vmcnt(0)
	v_lshlrev_b32_e32 v8, 16, v13
	v_lshlrev_b32_e32 v6, 16, v12
	v_lshlrev_b32_e32 v4, 16, v11
	v_lshlrev_b32_e32 v2, 16, v10
	v_and_b32_e32 v9, 0xffff0000, v13
	v_and_b32_e32 v7, 0xffff0000, v12
	v_and_b32_e32 v5, 0xffff0000, v11
	v_and_b32_e32 v3, 0xffff0000, v10
	global_load_dwordx4 v[54:57], v0, s[8:9] offset:16
	global_load_dwordx4 v[10:13], v0, s[8:9]
	global_load_dwordx4 v[62:65], v0, s[8:9] offset:2064
	global_load_dwordx4 v[66:69], v0, s[8:9] offset:2048
	global_load_dwordx4 v[70:73], v[58:59], off
	s_nop 0
	global_load_dwordx4 v[74:77], v[74:75], off offset:16
	s_nop 0
	global_load_dwordx4 v[78:81], v[58:59], off offset:2048
	s_nop 0
	global_load_dwordx4 v[82:85], v[82:83], off offset:16
	s_nop 0
	global_load_dwordx4 v[86:89], v0, s[6:7] offset:16
	global_load_dwordx4 v[106:109], v0, s[6:7]
	s_waitcnt vmcnt(1)
	v_pk_fma_f32 v[30:31], v[54:55], v[30:31], v[86:87]
	s_waitcnt vmcnt(0)
	v_pk_fma_f32 v[10:11], v[10:11], v[36:37], v[106:107]
	v_pk_fma_f32 v[12:13], v[12:13], v[34:35], v[108:109]
	v_pk_fma_f32 v[32:33], v[56:57], v[32:33], v[88:89]
	v_pk_fma_f32 v[10:11], v[66:67], v[44:45], v[10:11]
	v_pk_fma_f32 v[12:13], v[68:69], v[42:43], v[12:13]
	v_pk_fma_f32 v[30:31], v[62:63], v[40:41], v[30:31]
	v_pk_fma_f32 v[32:33], v[64:65], v[38:39], v[32:33]
	v_pk_fma_f32 v[10:11], v[70:71], v[52:53], v[10:11]
	v_pk_fma_f32 v[12:13], v[72:73], v[50:51], v[12:13]
	v_pk_fma_f32 v[30:31], v[74:75], v[48:49], v[30:31]
	v_pk_fma_f32 v[32:33], v[76:77], v[46:47], v[32:33]
	v_pk_fma_f32 v[10:11], v[78:79], v[2:3], v[10:11]
	v_pk_fma_f32 v[12:13], v[80:81], v[4:5], v[12:13]
	v_pk_fma_f32 v[30:31], v[82:83], v[6:7], v[30:31]
	v_pk_fma_f32 v[32:33], v[84:85], v[8:9], v[32:33]
	v_cvt_pk_bf16_f32 v10, v10, v11
	v_cvt_pk_bf16_f32 v11, v12, v13
	v_cvt_pk_bf16_f32 v12, v30, v31
	v_cvt_pk_bf16_f32 v13, v32, v33
	global_store_dwordx4 v[28:29], v[10:13], off sc1
	s_and_saveexec_b64 s[6:7], vcc
	s_cbranch_execz .LBB0_571
	v_ashrrev_i32_e32 v10, 12, v18
	v_add_u32_e32 v12, s62, v10
	v_add_u32_e32 v10, 0xfffff003, v20
	v_ashrrev_i32_e32 v11, 31, v10
	v_mad_i64_i32 v[10:11], s[8:9], v12, 3, v[10:11]
	v_readlane_b32 s8, v254, 7
	v_readlane_b32 s9, v254, 8
	s_load_dwordx2 s[8:9], s[8:9], 0x100
	v_add_u32_e32 v12, -13, v20
	v_mov_b32_e32 v13, v1
	v_lshl_add_u64 v[12:13], v[24:25], 0, v[12:13]
	v_mov_b32_e32 v15, 0x16b00000
	v_mov_b32_e32 v17, 0x16888000
	v_cndmask_b32_e64 v18, v15, v17, s[4:5]
	v_mov_b32_e32 v19, v1
	v_cndmask_b32_e64 v11, v13, v11, s[4:5]
	v_cndmask_b32_e64 v10, v12, v10, s[4:5]
	v_lshlrev_b64 v[10:11], 11, v[10:11]
	s_waitcnt lgkmcnt(0)
	v_lshl_add_u64 v[12:13], s[8:9], 0, v[18:19]
	v_lshl_add_u64 v[10:11], v[12:13], 0, v[10:11]
	v_lshl_add_u64 v[10:11], v[10:11], 0, v[0:1]
	global_store_dwordx4 v[10:11], v[6:9], off offset:16 sc1
	global_store_dwordx4 v[10:11], v[2:5], off sc1

.LBB0_674:
	s_or_b64 exec, exec, s[4:5]
	s_lshl_b64 s[4:5], s[50:51], 2
	v_mov_b32_e32 v3, v1
	s_add_u32 s4, s10, s4
	v_lshl_add_u64 v[42:43], v[6:7], 0, v[2:3]
	s_movk_i32 s0, 0x1000
	s_addc_u32 s5, s11, s5
	s_lshl_b64 s[6:7], s[48:49], 2
	v_add_co_u32_e32 v2, vcc, s0, v42
	s_add_u32 s6, s8, s6
	s_nop 0
	v_addc_co_u32_e32 v3, vcc, 0, v43, vcc
	s_movk_i32 s8, 0x5000
	v_add_co_u32_e32 v4, vcc, s8, v42
	s_mov_b32 s8, 0x8000
	s_nop 0
	v_addc_co_u32_e32 v5, vcc, 0, v43, vcc
	s_addc_u32 s7, s9, s7
	v_add_co_u32_e32 v30, vcc, s8, v42
	v_lshlrev_b32_e32 v0, 2, v98
	s_nop 0
	v_addc_co_u32_e32 v31, vcc, 0, v43, vcc
	v_lshl_add_u64 v[32:33], s[6:7], 0, v[0:1]
	v_add_co_u32_e32 v22, vcc, s0, v32
	s_mov_b32 s0, 0xc000
	s_nop 0
	v_addc_co_u32_e32 v23, vcc, 0, v33, vcc
	v_add_co_u32_e32 v34, vcc, s0, v42
	s_mov_b32 s0, 0xf000
	s_nop 0
	v_addc_co_u32_e32 v35, vcc, 0, v43, vcc
	global_load_dwordx4 v[154:157], v[2:3], off offset:2048
	global_load_dwordx4 v[74:77], v[4:5], off
	s_nop 0
	global_load_dwordx4 v[2:5], v0, s[6:7] offset:16
	global_load_dwordx4 v[10:13], v0, s[6:7]
	global_load_dwordx4 v[6:9], v0, s[6:7] offset:2064
	global_load_dwordx4 v[14:17], v0, s[6:7] offset:2048
	global_load_dwordx4 v[18:21], v[22:23], off
	global_load_dwordx4 v[26:29], v[22:23], off offset:2048
	s_nop 0
	global_load_dwordx4 v[22:25], v0, s[4:5] offset:16
	global_load_dwordx4 v[38:41], v0, s[4:5]
	v_add_co_u32_e32 v44, vcc, s0, v42
	s_mov_b64 s[4:5], 0x1000
	s_nop 0
	v_addc_co_u32_e32 v45, vcc, 0, v43, vcc
	s_mov_b32 s0, 0x13000
	global_load_dwordx4 v[70:73], v[30:31], off offset:2048
	global_load_dwordx4 v[58:61], v[34:35], off
	v_lshl_add_u64 v[30:31], v[32:33], 0, s[4:5]
	s_mov_b64 s[4:5], 0x1800
	v_add_co_u32_e32 v46, vcc, s0, v42
	v_lshl_add_u64 v[32:33], v[32:33], 0, s[4:5]
	s_nop 0
	v_addc_co_u32_e32 v47, vcc, 0, v43, vcc
	s_mov_b32 s0, 0x16000
	global_load_dwordx4 v[34:37], v[30:31], off offset:16
	s_nop 0
	global_load_dwordx4 v[30:33], v[32:33], off offset:16
	s_nop 0
	global_load_dwordx4 v[54:57], v[44:45], off offset:2048
	global_load_dwordx4 v[50:53], v[46:47], off
	v_add_co_u32_e32 v44, vcc, s0, v42
	s_mov_b32 s0, 0x1a000
	s_nop 0
	v_addc_co_u32_e32 v45, vcc, 0, v43, vcc
	v_add_co_u32_e32 v42, vcc, s0, v42
	s_waitcnt vmcnt(17)
	v_lshlrev_b32_e32 v86, 16, v62
	v_addc_co_u32_e32 v43, vcc, 0, v43, vcc
	global_load_dwordx4 v[46:49], v[44:45], off offset:2048
	s_nop 0
	global_load_dwordx4 v[42:45], v[42:43], off
	v_and_b32_e32 v87, 0xffff0000, v62
	v_mad_u64_u32 v[138:139], s[4:5], v84, 3, 0
	v_ashrrev_i32_e32 v84, 12, v82
	v_lshlrev_b32_e32 v158, 16, v63
	v_and_b32_e32 v159, 0xffff0000, v63
	v_lshlrev_b32_e32 v160, 16, v64
	v_and_b32_e32 v161, 0xffff0000, v64
	s_waitcnt vmcnt(18)
	v_lshlrev_b32_e32 v162, 16, v65
	v_and_b32_e32 v163, 0xffff0000, v65
	v_lshlrev_b32_e32 v88, 16, v66
	v_and_b32_e32 v89, 0xffff0000, v66
	v_add_u32_e32 v84, s62, v84
	v_lshlrev_b32_e32 v150, 16, v67
	v_and_b32_e32 v151, 0xffff0000, v67
	v_lshlrev_b32_e32 v146, 16, v78
	v_and_b32_e32 v147, 0xffff0000, v78
	v_mad_i32_i24 v139, v85, 3, v139
	v_mad_i64_i32 v[136:137], s[4:5], v84, 3, 0
	v_lshlrev_b32_e32 v84, 16, v68
	v_and_b32_e32 v85, 0xffff0000, v68
	v_lshlrev_b32_e32 v148, 16, v69
	v_and_b32_e32 v149, 0xffff0000, v69
	v_lshlrev_b32_e32 v144, 16, v79
	v_and_b32_e32 v145, 0xffff0000, v79
	v_lshlrev_b32_e32 v142, 16, v80
	v_and_b32_e32 v143, 0xffff0000, v80
	v_lshlrev_b32_e32 v140, 16, v81
	v_and_b32_e32 v141, 0xffff0000, v81
	v_cndmask_b32_e64 v107, 13, v207, s[46:47]
	v_lshlrev_b64 v[82:83], 10, v[82:83]
	v_lshl_add_u64 v[82:83], v[100:101], 0, v[82:83]
	v_cmp_ge_u32_e32 vcc, v106, v107
	s_waitcnt vmcnt(17)
	v_lshlrev_b32_e32 v62, 16, v154
	v_and_b32_e32 v63, 0xffff0000, v154
	s_waitcnt vmcnt(9)
	v_pk_fma_f32 v[68:69], v[2:3], v[160:161], v[22:23]
	s_waitcnt vmcnt(8)
	v_pk_fma_f32 v[64:65], v[10:11], v[86:87], v[38:39]
	v_pk_fma_f32 v[66:67], v[12:13], v[158:159], v[40:41]
	v_pk_fma_f32 v[64:65], v[14:15], v[88:89], v[64:65]
	v_pk_fma_f32 v[66:67], v[16:17], v[150:151], v[66:67]
	v_pk_fma_f32 v[64:65], v[18:19], v[146:147], v[64:65]
	v_pk_fma_f32 v[66:67], v[20:21], v[144:145], v[66:67]
	v_pk_fma_f32 v[78:79], v[26:27], v[62:63], v[64:65]
	v_lshlrev_b32_e32 v64, 16, v155
	v_and_b32_e32 v65, 0xffff0000, v155
	v_pk_fma_f32 v[68:69], v[6:7], v[84:85], v[68:69]
	v_pk_fma_f32 v[154:155], v[4:5], v[162:163], v[24:25]
	v_pk_fma_f32 v[80:81], v[28:29], v[64:65], v[66:67]
	v_lshlrev_b32_e32 v66, 16, v156
	v_and_b32_e32 v67, 0xffff0000, v156
	v_pk_fma_f32 v[154:155], v[8:9], v[148:149], v[154:155]
	s_waitcnt vmcnt(5)
	v_pk_fma_f32 v[68:69], v[34:35], v[142:143], v[68:69]
	v_pk_fma_f32 v[154:155], v[36:37], v[140:141], v[154:155]
	s_waitcnt vmcnt(4)
	v_pk_fma_f32 v[86:87], v[30:31], v[66:67], v[68:69]
	v_lshlrev_b32_e32 v68, 16, v157
	v_and_b32_e32 v69, 0xffff0000, v157
	v_pk_fma_f32 v[154:155], v[32:33], v[68:69], v[154:155]
	v_cvt_pk_bf16_f32 v78, v78, v79
	v_cvt_pk_bf16_f32 v79, v80, v81
	v_cvt_pk_bf16_f32 v80, v86, v87
	v_cvt_pk_bf16_f32 v81, v154, v155
	global_store_dwordx4 v[82:83], v[78:81], off sc1
	s_and_saveexec_b64 s[4:5], vcc
	s_cbranch_execz .LBB0_680
	s_and_saveexec_b64 s[6:7], s[44:45]
	s_xor_b64 s[6:7], exec, s[6:7]
	v_add_u32_e32 v78, -13, v106
	v_mov_b32_e32 v79, v1
	v_lshl_add_u64 v[78:79], v[138:139], 0, v[78:79]
	s_or_saveexec_b64 s[6:7], s[6:7]
	v_mov_b64_e32 v[80:81], 0x16b00000
	s_xor_b64 exec, exec, s[6:7]
	v_or_b32_e32 v78, 0xfffff003, v106
	v_ashrrev_i32_e32 v79, 31, v78
	v_lshl_add_u64 v[78:79], v[136:137], 0, v[78:79]
	v_mov_b64_e32 v[80:81], 0x16888000
	s_or_b64 exec, exec, s[6:7]
	v_lshl_add_u64 v[80:81], s[12:13], 0, v[80:81]
	v_lshlrev_b64 v[78:79], 11, v[78:79]
	v_lshl_add_u64 v[78:79], v[80:81], 0, v[78:79]
	v_lshl_add_u64 v[78:79], v[78:79], 0, v[0:1]
	global_store_dwordx4 v[78:79], v[62:65], off sc1
	global_store_dwordx4 v[78:79], v[66:69], off offset:16 sc1
.LBB0_680:
	s_or_b64 exec, exec, s[4:5]
	v_lshlrev_b32_e32 v86, 16, v74
	v_and_b32_e32 v87, 0xffff0000, v74
	v_pk_fma_f32 v[78:79], v[10:11], v[88:89], v[38:39]
	v_lshlrev_b32_e32 v88, 16, v75
	v_and_b32_e32 v89, 0xffff0000, v75
	v_pk_fma_f32 v[74:75], v[12:13], v[150:151], v[40:41]
	v_lshlrev_b32_e32 v82, 16, v76
	v_pk_fma_f32 v[74:75], v[16:17], v[144:145], v[74:75]
	v_and_b32_e32 v83, 0xffff0000, v76
	v_pk_fma_f32 v[74:75], v[20:21], v[64:65], v[74:75]
	v_pk_fma_f32 v[78:79], v[14:15], v[146:147], v[78:79]
	v_pk_fma_f32 v[80:81], v[28:29], v[88:89], v[74:75]
	v_pk_fma_f32 v[74:75], v[2:3], v[84:85], v[22:23]
	v_pk_fma_f32 v[78:79], v[18:19], v[62:63], v[78:79]
	v_pk_fma_f32 v[74:75], v[6:7], v[142:143], v[74:75]
	v_pk_fma_f32 v[78:79], v[26:27], v[86:87], v[78:79]
	v_pk_fma_f32 v[74:75], v[34:35], v[66:67], v[74:75]
	v_lshlrev_b32_e32 v84, 16, v77
	v_pk_fma_f32 v[150:151], v[30:31], v[82:83], v[74:75]
	v_pk_fma_f32 v[74:75], v[4:5], v[148:149], v[24:25]
	v_and_b32_e32 v85, 0xffff0000, v77
	v_pk_fma_f32 v[74:75], v[8:9], v[140:141], v[74:75]
	v_cvt_pk_bf16_f32 v76, v150, v151
	v_pk_fma_f32 v[74:75], v[36:37], v[68:69], v[74:75]
	v_cmp_ge_u32_e32 vcc, v110, v107
	v_pk_fma_f32 v[148:149], v[32:33], v[84:85], v[74:75]
	v_cvt_pk_bf16_f32 v74, v78, v79
	v_lshlrev_b64 v[78:79], 10, v[108:109]
	v_cvt_pk_bf16_f32 v75, v80, v81
	v_cvt_pk_bf16_f32 v77, v148, v149
	v_lshl_add_u64 v[78:79], v[100:101], 0, v[78:79]
	global_store_dwordx4 v[78:79], v[74:77], off sc1
	s_and_saveexec_b64 s[4:5], vcc
	s_cbranch_execz .LBB0_686
	s_and_saveexec_b64 s[6:7], s[44:45]
	s_xor_b64 s[6:7], exec, s[6:7]
	v_add_u32_e32 v74, -12, v106
	v_mov_b32_e32 v75, v1
	v_lshl_add_u64 v[74:75], v[138:139], 0, v[74:75]
	s_or_saveexec_b64 s[6:7], s[6:7]
	v_mov_b64_e32 v[76:77], 0x16b00000
	s_xor_b64 exec, exec, s[6:7]
	v_or_b32_e32 v74, 0xfffff004, v106
	v_ashrrev_i32_e32 v75, 31, v74
	v_lshl_add_u64 v[74:75], v[136:137], 0, v[74:75]
	v_mov_b64_e32 v[76:77], 0x16888000
	s_or_b64 exec, exec, s[6:7]
	v_lshl_add_u64 v[76:77], s[12:13], 0, v[76:77]
	v_lshlrev_b64 v[74:75], 11, v[74:75]
	v_lshl_add_u64 v[74:75], v[76:77], 0, v[74:75]
	v_lshl_add_u64 v[74:75], v[74:75], 0, v[0:1]
	global_store_dwordx4 v[74:75], v[86:89], off sc1
	global_store_dwordx4 v[74:75], v[82:85], off offset:16 sc1
.LBB0_686:
	s_or_b64 exec, exec, s[4:5]
	v_lshlrev_b32_e32 v78, 16, v70
	v_and_b32_e32 v79, 0xffff0000, v70
	v_lshlrev_b32_e32 v80, 16, v71
	v_and_b32_e32 v81, 0xffff0000, v71
	v_pk_fma_f32 v[70:71], v[12:13], v[144:145], v[40:41]
	v_pk_fma_f32 v[74:75], v[10:11], v[146:147], v[38:39]
	v_pk_fma_f32 v[70:71], v[16:17], v[64:65], v[70:71]
	v_pk_fma_f32 v[74:75], v[14:15], v[62:63], v[74:75]
	v_pk_fma_f32 v[70:71], v[20:21], v[88:89], v[70:71]
	v_pk_fma_f32 v[74:75], v[18:19], v[86:87], v[74:75]
	v_pk_fma_f32 v[110:111], v[28:29], v[80:81], v[70:71]
	v_pk_fma_f32 v[70:71], v[2:3], v[142:143], v[22:23]
	v_pk_fma_f32 v[108:109], v[26:27], v[78:79], v[74:75]
	v_pk_fma_f32 v[70:71], v[6:7], v[66:67], v[70:71]
	v_lshlrev_b32_e32 v74, 16, v72
	v_and_b32_e32 v75, 0xffff0000, v72
	v_pk_fma_f32 v[70:71], v[34:35], v[82:83], v[70:71]
	v_lshlrev_b32_e32 v76, 16, v73
	v_pk_fma_f32 v[142:143], v[30:31], v[74:75], v[70:71]
	v_pk_fma_f32 v[70:71], v[4:5], v[140:141], v[24:25]
	v_and_b32_e32 v77, 0xffff0000, v73
	v_pk_fma_f32 v[70:71], v[8:9], v[68:69], v[70:71]
	v_cvt_pk_bf16_f32 v72, v142, v143
	v_pk_fma_f32 v[70:71], v[36:37], v[84:85], v[70:71]
	v_cmp_ge_u32_e32 vcc, v114, v107
	v_pk_fma_f32 v[140:141], v[32:33], v[76:77], v[70:71]
	v_cvt_pk_bf16_f32 v70, v108, v109
	v_lshlrev_b64 v[108:109], 10, v[112:113]
	v_cvt_pk_bf16_f32 v71, v110, v111
	v_cvt_pk_bf16_f32 v73, v140, v141
	v_lshl_add_u64 v[108:109], v[100:101], 0, v[108:109]
	global_store_dwordx4 v[108:109], v[70:73], off sc1
	s_and_saveexec_b64 s[4:5], vcc
	s_cbranch_execz .LBB0_692
	s_and_saveexec_b64 s[6:7], s[44:45]
	s_xor_b64 s[6:7], exec, s[6:7]
	v_add_u32_e32 v70, -11, v106
	v_mov_b32_e32 v71, v1
	v_lshl_add_u64 v[70:71], v[138:139], 0, v[70:71]
	s_or_saveexec_b64 s[6:7], s[6:7]
	v_mov_b64_e32 v[72:73], 0x16b00000
	s_xor_b64 exec, exec, s[6:7]
	v_or_b32_e32 v70, 0xfffff005, v106
	v_ashrrev_i32_e32 v71, 31, v70
	v_lshl_add_u64 v[70:71], v[136:137], 0, v[70:71]
	v_mov_b64_e32 v[72:73], 0x16888000
	s_or_b64 exec, exec, s[6:7]
	v_lshl_add_u64 v[72:73], s[12:13], 0, v[72:73]
	v_lshlrev_b64 v[70:71], 11, v[70:71]
	v_lshl_add_u64 v[70:71], v[72:73], 0, v[70:71]
	v_lshl_add_u64 v[70:71], v[70:71], 0, v[0:1]
	global_store_dwordx4 v[70:71], v[78:81], off sc1
	global_store_dwordx4 v[70:71], v[74:77], off offset:16 sc1
.LBB0_692:
	s_or_b64 exec, exec, s[4:5]
	v_lshlrev_b32_e32 v70, 16, v58
	v_and_b32_e32 v71, 0xffff0000, v58
	v_lshlrev_b32_e32 v72, 16, v59
	v_and_b32_e32 v73, 0xffff0000, v59
	v_pk_fma_f32 v[58:59], v[12:13], v[64:65], v[40:41]
	v_pk_fma_f32 v[62:63], v[10:11], v[62:63], v[38:39]
	v_pk_fma_f32 v[58:59], v[16:17], v[88:89], v[58:59]
	v_pk_fma_f32 v[62:63], v[14:15], v[86:87], v[62:63]
	v_pk_fma_f32 v[58:59], v[20:21], v[80:81], v[58:59]
	v_pk_fma_f32 v[62:63], v[18:19], v[78:79], v[62:63]
	v_pk_fma_f32 v[110:111], v[28:29], v[72:73], v[58:59]
	v_pk_fma_f32 v[58:59], v[2:3], v[66:67], v[22:23]
	v_pk_fma_f32 v[108:109], v[26:27], v[70:71], v[62:63]
	v_pk_fma_f32 v[58:59], v[6:7], v[82:83], v[58:59]
	v_lshlrev_b32_e32 v62, 16, v60
	v_and_b32_e32 v63, 0xffff0000, v60
	v_pk_fma_f32 v[58:59], v[34:35], v[74:75], v[58:59]
	v_lshlrev_b32_e32 v64, 16, v61
	v_pk_fma_f32 v[66:67], v[30:31], v[62:63], v[58:59]
	v_pk_fma_f32 v[58:59], v[4:5], v[68:69], v[24:25]
	v_and_b32_e32 v65, 0xffff0000, v61
	v_pk_fma_f32 v[58:59], v[8:9], v[84:85], v[58:59]
	v_cvt_pk_bf16_f32 v60, v66, v67
	v_pk_fma_f32 v[58:59], v[36:37], v[76:77], v[58:59]
	v_lshlrev_b64 v[66:67], 10, v[116:117]
	v_pk_fma_f32 v[68:69], v[32:33], v[64:65], v[58:59]
	v_cvt_pk_bf16_f32 v58, v108, v109
	v_cvt_pk_bf16_f32 v59, v110, v111
	v_cvt_pk_bf16_f32 v61, v68, v69
	v_lshl_add_u64 v[66:67], v[100:101], 0, v[66:67]
	v_cmp_ge_u32_e32 vcc, v118, v107
	global_store_dwordx4 v[66:67], v[58:61], off sc1
	s_and_saveexec_b64 s[4:5], vcc
	s_cbranch_execz .LBB0_698
	s_and_saveexec_b64 s[6:7], s[44:45]
	s_xor_b64 s[6:7], exec, s[6:7]
	v_add_u32_e32 v58, -10, v106
	v_mov_b32_e32 v59, v1
	v_lshl_add_u64 v[58:59], v[138:139], 0, v[58:59]
	s_or_saveexec_b64 s[6:7], s[6:7]
	v_mov_b64_e32 v[60:61], 0x16b00000
	s_xor_b64 exec, exec, s[6:7]
	v_or_b32_e32 v58, 0xfffff006, v106
	v_ashrrev_i32_e32 v59, 31, v58
	v_lshl_add_u64 v[58:59], v[136:137], 0, v[58:59]
	v_mov_b64_e32 v[60:61], 0x16888000
	s_or_b64 exec, exec, s[6:7]
	v_lshl_add_u64 v[60:61], s[12:13], 0, v[60:61]
	v_lshlrev_b64 v[58:59], 11, v[58:59]
	v_lshl_add_u64 v[58:59], v[60:61], 0, v[58:59]
	v_lshl_add_u64 v[58:59], v[58:59], 0, v[0:1]
	global_store_dwordx4 v[58:59], v[70:73], off sc1
	global_store_dwordx4 v[58:59], v[62:65], off offset:16 sc1
.LBB0_698:
	s_or_b64 exec, exec, s[4:5]
	v_pk_fma_f32 v[60:61], v[10:11], v[86:87], v[38:39]
	s_waitcnt vmcnt(7)
	v_lshlrev_b32_e32 v58, 16, v54
	v_pk_fma_f32 v[60:61], v[14:15], v[78:79], v[60:61]
	v_and_b32_e32 v59, 0xffff0000, v54
	v_pk_fma_f32 v[60:61], v[18:19], v[70:71], v[60:61]
	v_pk_fma_f32 v[82:83], v[2:3], v[82:83], v[22:23]
	v_pk_fma_f32 v[66:67], v[26:27], v[58:59], v[60:61]
	v_lshlrev_b32_e32 v60, 16, v55
	v_and_b32_e32 v61, 0xffff0000, v55
	v_pk_fma_f32 v[54:55], v[12:13], v[88:89], v[40:41]
	v_pk_fma_f32 v[82:83], v[6:7], v[74:75], v[82:83]
	v_pk_fma_f32 v[54:55], v[16:17], v[80:81], v[54:55]
	v_pk_fma_f32 v[84:85], v[4:5], v[84:85], v[24:25]
	v_pk_fma_f32 v[54:55], v[20:21], v[72:73], v[54:55]
	v_pk_fma_f32 v[82:83], v[34:35], v[62:63], v[82:83]
	v_pk_fma_f32 v[68:69], v[28:29], v[60:61], v[54:55]
	v_lshlrev_b32_e32 v54, 16, v56
	v_and_b32_e32 v55, 0xffff0000, v56
	v_pk_fma_f32 v[84:85], v[8:9], v[76:77], v[84:85]
	v_pk_fma_f32 v[82:83], v[30:31], v[54:55], v[82:83]
	v_lshlrev_b32_e32 v56, 16, v57
	v_and_b32_e32 v57, 0xffff0000, v57
	v_pk_fma_f32 v[84:85], v[36:37], v[64:65], v[84:85]
	v_cvt_pk_bf16_f32 v66, v66, v67
	v_pk_fma_f32 v[84:85], v[32:33], v[56:57], v[84:85]
	v_cvt_pk_bf16_f32 v67, v68, v69
	v_cvt_pk_bf16_f32 v68, v82, v83
	v_lshlrev_b64 v[82:83], 10, v[120:121]
	v_cvt_pk_bf16_f32 v69, v84, v85
	v_lshl_add_u64 v[82:83], v[100:101], 0, v[82:83]
	v_cmp_ge_u32_e32 vcc, v122, v107
	global_store_dwordx4 v[82:83], v[66:69], off sc1
	s_and_saveexec_b64 s[4:5], vcc
	s_cbranch_execz .LBB0_704
	s_and_saveexec_b64 s[6:7], s[44:45]
	s_xor_b64 s[6:7], exec, s[6:7]
	v_add_u32_e32 v66, -9, v106
	v_mov_b32_e32 v67, v1
	v_lshl_add_u64 v[66:67], v[138:139], 0, v[66:67]
	s_or_saveexec_b64 s[6:7], s[6:7]
	v_mov_b64_e32 v[68:69], 0x16b00000
	s_xor_b64 exec, exec, s[6:7]
	v_or_b32_e32 v66, 0xfffff007, v106
	v_ashrrev_i32_e32 v67, 31, v66
	v_lshl_add_u64 v[66:67], v[136:137], 0, v[66:67]
	v_mov_b64_e32 v[68:69], 0x16888000
	s_or_b64 exec, exec, s[6:7]
	v_lshl_add_u64 v[68:69], s[12:13], 0, v[68:69]
	v_lshlrev_b64 v[66:67], 11, v[66:67]
	v_lshl_add_u64 v[66:67], v[68:69], 0, v[66:67]
	v_lshl_add_u64 v[66:67], v[66:67], 0, v[0:1]
	global_store_dwordx4 v[66:67], v[58:61], off sc1
	global_store_dwordx4 v[66:67], v[54:57], off offset:16 sc1
.LBB0_704:
	s_or_b64 exec, exec, s[4:5]
	v_pk_fma_f32 v[68:69], v[10:11], v[78:79], v[38:39]
	s_waitcnt vmcnt(7)
	v_lshlrev_b32_e32 v66, 16, v50
	v_pk_fma_f32 v[68:69], v[14:15], v[70:71], v[68:69]
	v_and_b32_e32 v67, 0xffff0000, v50
	v_pk_fma_f32 v[68:69], v[18:19], v[58:59], v[68:69]
	v_pk_fma_f32 v[74:75], v[2:3], v[74:75], v[22:23]
	v_pk_fma_f32 v[78:79], v[26:27], v[66:67], v[68:69]
	v_lshlrev_b32_e32 v68, 16, v51
	v_and_b32_e32 v69, 0xffff0000, v51
	v_pk_fma_f32 v[50:51], v[12:13], v[80:81], v[40:41]
	v_pk_fma_f32 v[74:75], v[6:7], v[62:63], v[74:75]
	v_pk_fma_f32 v[50:51], v[16:17], v[72:73], v[50:51]
	v_pk_fma_f32 v[74:75], v[34:35], v[54:55], v[74:75]
	v_pk_fma_f32 v[50:51], v[20:21], v[60:61], v[50:51]
	v_cmp_ge_u32_e32 vcc, v126, v107
	v_pk_fma_f32 v[80:81], v[28:29], v[68:69], v[50:51]
	v_lshlrev_b32_e32 v50, 16, v52
	v_and_b32_e32 v51, 0xffff0000, v52
	v_pk_fma_f32 v[82:83], v[30:31], v[50:51], v[74:75]
	v_pk_fma_f32 v[74:75], v[4:5], v[76:77], v[24:25]
	v_lshlrev_b32_e32 v52, 16, v53
	v_pk_fma_f32 v[74:75], v[8:9], v[64:65], v[74:75]
	v_and_b32_e32 v53, 0xffff0000, v53
	v_pk_fma_f32 v[74:75], v[36:37], v[56:57], v[74:75]
	v_cvt_pk_bf16_f32 v76, v82, v83
	v_pk_fma_f32 v[84:85], v[32:33], v[52:53], v[74:75]
	v_cvt_pk_bf16_f32 v74, v78, v79
	v_lshlrev_b64 v[78:79], 10, v[124:125]
	v_cvt_pk_bf16_f32 v75, v80, v81
	v_cvt_pk_bf16_f32 v77, v84, v85
	v_lshl_add_u64 v[78:79], v[100:101], 0, v[78:79]
	global_store_dwordx4 v[78:79], v[74:77], off sc1
	s_and_saveexec_b64 s[4:5], vcc
	s_cbranch_execz .LBB0_710
	s_and_saveexec_b64 s[6:7], s[44:45]
	s_xor_b64 s[6:7], exec, s[6:7]
	v_add_u32_e32 v74, -8, v106
	v_mov_b32_e32 v75, v1
	v_lshl_add_u64 v[74:75], v[138:139], 0, v[74:75]
	s_or_saveexec_b64 s[6:7], s[6:7]
	v_mov_b64_e32 v[76:77], 0x16b00000
	s_xor_b64 exec, exec, s[6:7]
	v_add_u32_e32 v74, 0xfffff008, v106
	v_ashrrev_i32_e32 v75, 31, v74
	v_lshl_add_u64 v[74:75], v[136:137], 0, v[74:75]
	v_mov_b64_e32 v[76:77], 0x16888000
	s_or_b64 exec, exec, s[6:7]
	v_lshl_add_u64 v[76:77], s[12:13], 0, v[76:77]
	v_lshlrev_b64 v[74:75], 11, v[74:75]
	v_lshl_add_u64 v[74:75], v[76:77], 0, v[74:75]
	v_lshl_add_u64 v[74:75], v[74:75], 0, v[0:1]
	global_store_dwordx4 v[74:75], v[66:69], off sc1
	global_store_dwordx4 v[74:75], v[50:53], off offset:16 sc1
.LBB0_710:
	s_or_b64 exec, exec, s[4:5]
	s_waitcnt vmcnt(7)
	v_lshlrev_b32_e32 v74, 16, v46
	v_and_b32_e32 v75, 0xffff0000, v46
	v_lshlrev_b32_e32 v76, 16, v47
	v_and_b32_e32 v77, 0xffff0000, v47
	v_pk_fma_f32 v[46:47], v[12:13], v[72:73], v[40:41]
	v_pk_fma_f32 v[62:63], v[2:3], v[62:63], v[22:23]
	v_pk_fma_f32 v[46:47], v[16:17], v[60:61], v[46:47]
	v_pk_fma_f32 v[62:63], v[6:7], v[54:55], v[62:63]
	v_pk_fma_f32 v[46:47], v[20:21], v[68:69], v[46:47]
	v_pk_fma_f32 v[70:71], v[10:11], v[70:71], v[38:39]
	v_pk_fma_f32 v[72:73], v[28:29], v[76:77], v[46:47]
	v_lshlrev_b32_e32 v46, 16, v48
	v_and_b32_e32 v47, 0xffff0000, v48
	v_pk_fma_f32 v[62:63], v[34:35], v[50:51], v[62:63]
	v_pk_fma_f32 v[70:71], v[14:15], v[58:59], v[70:71]
	v_pk_fma_f32 v[78:79], v[30:31], v[46:47], v[62:63]
	v_pk_fma_f32 v[62:63], v[4:5], v[64:65], v[24:25]
	v_pk_fma_f32 v[70:71], v[18:19], v[66:67], v[70:71]
	v_pk_fma_f32 v[62:63], v[8:9], v[56:57], v[62:63]
	v_pk_fma_f32 v[70:71], v[26:27], v[74:75], v[70:71]
	v_lshlrev_b32_e32 v48, 16, v49
	v_and_b32_e32 v49, 0xffff0000, v49
	v_pk_fma_f32 v[62:63], v[36:37], v[52:53], v[62:63]
	v_cvt_pk_bf16_f32 v64, v78, v79
	v_pk_fma_f32 v[80:81], v[32:33], v[48:49], v[62:63]
	v_cvt_pk_bf16_f32 v62, v70, v71
	v_lshlrev_b64 v[70:71], 10, v[128:129]
	v_cvt_pk_bf16_f32 v63, v72, v73
	v_cvt_pk_bf16_f32 v65, v80, v81
	v_lshl_add_u64 v[70:71], v[100:101], 0, v[70:71]
	v_cmp_ge_u32_e32 vcc, v130, v107
	global_store_dwordx4 v[70:71], v[62:65], off sc1
	s_and_saveexec_b64 s[4:5], vcc
	s_cbranch_execz .LBB0_716
	s_and_saveexec_b64 s[6:7], s[44:45]
	s_xor_b64 s[6:7], exec, s[6:7]
	v_add_u32_e32 v62, -7, v106
	v_mov_b32_e32 v63, v1
	v_lshl_add_u64 v[62:63], v[138:139], 0, v[62:63]
	s_or_saveexec_b64 s[6:7], s[6:7]
	v_mov_b64_e32 v[64:65], 0x16b00000
	s_xor_b64 exec, exec, s[6:7]
	v_add_u32_e32 v62, 0xfffff009, v106
	v_ashrrev_i32_e32 v63, 31, v62
	v_lshl_add_u64 v[62:63], v[136:137], 0, v[62:63]
	v_mov_b64_e32 v[64:65], 0x16888000
	s_or_b64 exec, exec, s[6:7]
	v_lshl_add_u64 v[64:65], s[12:13], 0, v[64:65]
	v_lshlrev_b64 v[62:63], 11, v[62:63]
	v_lshl_add_u64 v[62:63], v[64:65], 0, v[62:63]
	v_lshl_add_u64 v[62:63], v[62:63], 0, v[0:1]
	global_store_dwordx4 v[62:63], v[74:77], off sc1
	global_store_dwordx4 v[62:63], v[46:49], off offset:16 sc1
.LBB0_716:
	s_or_b64 exec, exec, s[4:5]
	v_pk_fma_f32 v[2:3], v[2:3], v[54:55], v[22:23]
	s_waitcnt vmcnt(7)
	v_lshlrev_b32_e32 v70, 16, v44
	v_pk_fma_f32 v[2:3], v[6:7], v[50:51], v[2:3]
	v_and_b32_e32 v71, 0xffff0000, v44
	v_pk_fma_f32 v[2:3], v[34:35], v[46:47], v[2:3]
	v_pk_fma_f32 v[10:11], v[10:11], v[58:59], v[38:39]
	v_pk_fma_f32 v[12:13], v[12:13], v[60:61], v[40:41]
	v_pk_fma_f32 v[6:7], v[30:31], v[70:71], v[2:3]
	v_pk_fma_f32 v[2:3], v[4:5], v[56:57], v[24:25]
	v_pk_fma_f32 v[10:11], v[14:15], v[66:67], v[10:11]
	v_pk_fma_f32 v[12:13], v[16:17], v[68:69], v[12:13]
	v_pk_fma_f32 v[2:3], v[8:9], v[52:53], v[2:3]
	v_lshlrev_b32_e32 v72, 16, v45
	v_lshlrev_b32_e32 v64, 16, v43
	v_lshlrev_b32_e32 v62, 16, v42
	v_and_b32_e32 v73, 0xffff0000, v45
	v_and_b32_e32 v65, 0xffff0000, v43
	v_and_b32_e32 v63, 0xffff0000, v42
	v_pk_fma_f32 v[10:11], v[18:19], v[74:75], v[10:11]
	v_pk_fma_f32 v[12:13], v[20:21], v[76:77], v[12:13]
	v_pk_fma_f32 v[2:3], v[36:37], v[48:49], v[2:3]
	v_pk_fma_f32 v[10:11], v[26:27], v[62:63], v[10:11]
	v_pk_fma_f32 v[12:13], v[28:29], v[64:65], v[12:13]
	v_pk_fma_f32 v[8:9], v[32:33], v[72:73], v[2:3]
	v_cvt_pk_bf16_f32 v4, v6, v7
	v_lshlrev_b64 v[6:7], 10, v[132:133]
	v_cvt_pk_bf16_f32 v2, v10, v11
	v_cvt_pk_bf16_f32 v3, v12, v13
	v_cvt_pk_bf16_f32 v5, v8, v9
	v_lshl_add_u64 v[6:7], v[100:101], 0, v[6:7]
	v_cmp_ge_u32_e32 vcc, v134, v107
	global_store_dwordx4 v[6:7], v[2:5], off sc1
	s_and_saveexec_b64 s[4:5], vcc
	s_cbranch_execz .LBB0_722
	s_and_saveexec_b64 s[6:7], s[44:45]
	s_xor_b64 s[6:7], exec, s[6:7]
	v_add_u32_e32 v2, -6, v106
	v_mov_b32_e32 v3, v1
	v_lshl_add_u64 v[2:3], v[138:139], 0, v[2:3]
	s_or_saveexec_b64 s[6:7], s[6:7]
	v_mov_b64_e32 v[4:5], 0x16b00000
	s_xor_b64 exec, exec, s[6:7]
	v_add_u32_e32 v2, 0xfffff00a, v106
	v_ashrrev_i32_e32 v3, 31, v2
	v_lshl_add_u64 v[2:3], v[136:137], 0, v[2:3]
	v_mov_b64_e32 v[4:5], 0x16888000
	s_or_b64 exec, exec, s[6:7]
	v_lshl_add_u64 v[4:5], s[12:13], 0, v[4:5]
	v_lshlrev_b64 v[2:3], 11, v[2:3]
	v_lshl_add_u64 v[2:3], v[4:5], 0, v[2:3]
	v_lshl_add_u64 v[2:3], v[2:3], 0, v[0:1]
	global_store_dwordx4 v[2:3], v[70:73], off offset:16 sc1
	global_store_dwordx4 v[2:3], v[62:65], off sc1

.Lpf0_742_goP:
	v_cvt_pk_bf16_f32 v2, v100, s0
	v_cvt_pk_bf16_f32 v3, v101, s0
	v_cvt_pk_bf16_f32 v4, v102, s0
	v_cvt_pk_bf16_f32 v5, v103, s0
	ds_write_b16 v12, v2
	ds_write_b16 v12, v3 offset:144
	ds_write_b16 v12, v4 offset:288
	ds_write_b16 v12, v5 offset:432
	s_waitcnt lgkmcnt(0)
	s_barrier
	s_and_saveexec_b64 s[48:49], s[4:5]
	s_cbranch_execz .Lpf0_742_latchP
	s_add_i32 s47, s46, 0x60
	s_cmpk_lt_i32 s46, 0x1a0
	s_cselect_b32 s46, s46, s47
	v_add_u32_e32 v6, s46, v11
	ds_read_b128 v[2:5], v14
	v_ashrrev_i32_e32 v7, 31, v6
	v_lshlrev_b64 v[6:7], 11, v[6:7]
	v_lshl_add_u64 v[6:7], s[44:45], 0, v[6:7]
	s_lshl_b32 s0, s0, 1
	v_lshl_add_u64 v[6:7], v[6:7], 0, s[0:1]
	v_lshlrev_b32_e32 v8, 1, v13
	v_mov_b32_e32 v9, v1
	v_lshl_add_u64 v[6:7], v[6:7], 0, v[8:9]
	s_waitcnt lgkmcnt(0)
	global_store_dwordx4 v[6:7], v[2:5], off sc1

.Lpf0_742_goQ:
	v_cvt_pk_bf16_f32 v2, v104, s0
	v_cvt_pk_bf16_f32 v3, v105, s0
	v_cvt_pk_bf16_f32 v4, v106, s0
	v_cvt_pk_bf16_f32 v5, v107, s0
	ds_write_b16 v12, v2
	ds_write_b16 v12, v3 offset:144
	ds_write_b16 v12, v4 offset:288
	ds_write_b16 v12, v5 offset:432
	s_waitcnt lgkmcnt(0)
	s_barrier
	s_and_saveexec_b64 s[48:49], s[4:5]
	s_cbranch_execz .Lpf0_742_latchQ
	s_add_i32 s47, s46, 0x60
	s_cmpk_lt_i32 s46, 0x1a0
	s_cselect_b32 s46, s46, s47
	v_add_u32_e32 v6, s46, v11
	ds_read_b128 v[2:5], v14
	v_ashrrev_i32_e32 v7, 31, v6
	v_lshlrev_b64 v[6:7], 11, v[6:7]
	v_lshl_add_u64 v[6:7], s[44:45], 0, v[6:7]
	s_lshl_b32 s0, s0, 1
	v_lshl_add_u64 v[6:7], v[6:7], 0, s[0:1]
	v_lshlrev_b32_e32 v8, 1, v13
	v_mov_b32_e32 v9, v1
	v_lshl_add_u64 v[6:7], v[6:7], 0, v[8:9]
	s_waitcnt lgkmcnt(0)
	global_store_dwordx4 v[6:7], v[2:5], off sc1

.LBB0_746:
	v_lshl_add_u64 v[8:9], v[8:9], 0, s[48:49]
	v_mov_b32_e32 v4, v2
	v_mov_b32_e32 v5, v3
	v_cmp_lt_i64_e32 vcc, s[52:53], v[8:9]
	global_store_dwordx4 v[6:7], v[2:5], off sc1
	s_or_b64 s[46:47], vcc, s[46:47]
	v_lshl_add_u64 v[6:7], v[6:7], 0, s[50:51]
	s_andn2_b64 exec, exec, s[46:47]
	s_cbranch_execnz .LBB0_746

.LBB0_750:
	s_and_b32 s0, s52, 0x1c0
	v_add_u32_e32 v2, s0, v11
	v_ashrrev_i32_e32 v3, 31, v2
	s_and_b32 s48, s53, 0xffffffe0
	v_lshlrev_b64 v[2:3], 12, v[2:3]
	v_lshl_add_u64 v[2:3], s[6:7], 0, v[2:3]
	s_ashr_i32 s49, s48, 31
	v_lshl_add_u64 v[2:3], s[48:49], 2, v[2:3]
	v_lshl_add_u64 v[2:3], v[2:3], 0, v[0:1]
	global_load_dwordx4 v[2:5], v[2:3], off
	s_waitcnt vmcnt(0)
	v_cvt_pk_bf16_f32 v2, v2, s0
	v_cvt_pk_bf16_f32 v3, v3, s0
	v_cvt_pk_bf16_f32 v4, v4, s0
	v_cvt_pk_bf16_f32 v5, v5, s0
	ds_write_b16 v12, v2
	ds_write_b16 v12, v3 offset:144
	ds_write_b16 v12, v4 offset:288
	ds_write_b16 v12, v5 offset:432
	s_waitcnt lgkmcnt(0)
	s_barrier
	s_and_saveexec_b64 s[50:51], s[4:5]
	s_cbranch_execz .LBB0_749
	v_add_u32_e32 v2, s48, v11
	v_ashrrev_i32_e32 v3, 31, v2
	v_lshlrev_b64 v[2:3], 10, v[2:3]
	v_lshl_add_u64 v[6:7], s[46:47], 0, v[2:3]
	ds_read_b128 v[2:5], v14
	s_lshl_b32 s0, s0, 1
	v_lshl_add_u64 v[6:7], v[6:7], 0, s[0:1]
	v_lshlrev_b32_e32 v8, 1, v13
	v_mov_b32_e32 v9, v1
	v_lshl_add_u64 v[6:7], v[6:7], 0, v[8:9]
	s_waitcnt lgkmcnt(0)
	global_store_dwordx4 v[6:7], v[2:5], off sc1
	s_branch .LBB0_749

.LBB0_754:
	s_and_b32 s0, s52, 0x1c0
	v_add_u32_e32 v2, s0, v11
	v_ashrrev_i32_e32 v3, 31, v2
	s_and_b32 s48, s53, 0xffffffe0
	v_lshlrev_b64 v[2:3], 12, v[2:3]
	v_lshl_add_u64 v[2:3], s[46:47], 0, v[2:3]
	s_ashr_i32 s49, s48, 31
	v_lshl_add_u64 v[2:3], s[48:49], 2, v[2:3]
	v_lshl_add_u64 v[2:3], v[2:3], 0, v[0:1]
	global_load_dwordx4 v[2:5], v[2:3], off
	s_waitcnt vmcnt(0)
	v_cvt_pk_bf16_f32 v2, v2, s0
	v_cvt_pk_bf16_f32 v3, v3, s0
	v_cvt_pk_bf16_f32 v4, v4, s0
	v_cvt_pk_bf16_f32 v5, v5, s0
	ds_write_b16 v12, v2
	ds_write_b16 v12, v3 offset:144
	ds_write_b16 v12, v4 offset:288
	ds_write_b16 v12, v5 offset:432
	s_waitcnt lgkmcnt(0)
	s_barrier
	s_and_saveexec_b64 s[50:51], s[4:5]
	s_cbranch_execz .LBB0_753
	v_add_u32_e32 v2, s48, v11
	v_ashrrev_i32_e32 v3, 31, v2
	v_lshlrev_b64 v[2:3], 10, v[2:3]
	v_lshl_add_u64 v[6:7], s[6:7], 0, v[2:3]
	ds_read_b128 v[2:5], v14
	s_lshl_b32 s0, s0, 1
	v_lshl_add_u64 v[6:7], v[6:7], 0, s[0:1]
	v_lshlrev_b32_e32 v8, 1, v13
	v_mov_b32_e32 v9, v1
	v_lshl_add_u64 v[6:7], v[6:7], 0, v[8:9]
	s_waitcnt lgkmcnt(0)
	global_store_dwordx4 v[6:7], v[2:5], off sc1
	s_branch .LBB0_753

.LBB0_758:
	s_and_b32 s0, s50, 0x1c0
	v_add_u32_e32 v2, s0, v11
	v_ashrrev_i32_e32 v3, 31, v2
	s_and_b32 s46, s51, 0xffffffe0
	v_lshlrev_b64 v[2:3], 12, v[2:3]
	v_lshl_add_u64 v[2:3], s[6:7], 0, v[2:3]
	s_ashr_i32 s47, s46, 31
	v_lshl_add_u64 v[2:3], s[46:47], 2, v[2:3]
	v_lshl_add_u64 v[2:3], v[2:3], 0, v[0:1]
	global_load_dwordx4 v[2:5], v[2:3], off
	s_waitcnt vmcnt(0)
	v_cvt_pk_bf16_f32 v2, v2, s0
	v_cvt_pk_bf16_f32 v3, v3, s0
	v_cvt_pk_bf16_f32 v4, v4, s0
	v_cvt_pk_bf16_f32 v5, v5, s0
	ds_write_b16 v12, v2
	ds_write_b16 v12, v3 offset:144
	ds_write_b16 v12, v4 offset:288
	ds_write_b16 v12, v5 offset:432
	s_waitcnt lgkmcnt(0)
	s_barrier
	s_and_saveexec_b64 s[48:49], s[4:5]
	s_cbranch_execz .LBB0_757
	v_add_u32_e32 v2, s46, v11
	v_ashrrev_i32_e32 v3, 31, v2
	v_lshlrev_b64 v[2:3], 10, v[2:3]
	v_lshl_add_u64 v[6:7], s[24:25], 0, v[2:3]
	ds_read_b128 v[2:5], v14
	s_lshl_b32 s0, s0, 1
	v_lshl_add_u64 v[6:7], v[6:7], 0, s[0:1]
	v_lshlrev_b32_e32 v8, 1, v13
	v_mov_b32_e32 v9, v1
	v_lshl_add_u64 v[6:7], v[6:7], 0, v[8:9]
	s_waitcnt lgkmcnt(0)
	global_store_dwordx4 v[6:7], v[2:5], off sc1
	s_branch .LBB0_757

.LBB0_763:
	s_and_b32 s0, s48, 0x3c0
	v_add_u32_e32 v2, s0, v11
	v_ashrrev_i32_e32 v3, 31, v2
	s_and_b32 s26, s49, 0xffffffe0
	v_lshlrev_b64 v[2:3], 12, v[2:3]
	v_lshl_add_u64 v[2:3], s[6:7], 0, v[2:3]
	s_ashr_i32 s27, s26, 31
	v_lshl_add_u64 v[2:3], s[26:27], 2, v[2:3]
	v_lshl_add_u64 v[2:3], v[2:3], 0, v[0:1]
	global_load_dwordx4 v[2:5], v[2:3], off
	s_waitcnt vmcnt(0)
	v_cvt_pk_bf16_f32 v2, v2, s0
	v_cvt_pk_bf16_f32 v3, v3, s0
	v_cvt_pk_bf16_f32 v4, v4, s0
	v_cvt_pk_bf16_f32 v5, v5, s0
	ds_write_b16 v12, v2
	ds_write_b16 v12, v3 offset:144
	ds_write_b16 v12, v4 offset:288
	ds_write_b16 v12, v5 offset:432
	s_waitcnt lgkmcnt(0)
	s_barrier
	s_and_saveexec_b64 s[46:47], s[4:5]
	s_cbranch_execz .LBB0_762
	v_add_u32_e32 v2, s26, v11
	v_ashrrev_i32_e32 v3, 31, v2
	v_lshlrev_b64 v[2:3], 11, v[2:3]
	v_lshl_add_u64 v[6:7], s[24:25], 0, v[2:3]
	ds_read_b128 v[2:5], v14
	s_lshl_b32 s0, s0, 1
	v_lshl_add_u64 v[6:7], v[6:7], 0, s[0:1]
	v_lshlrev_b32_e32 v8, 1, v13
	v_mov_b32_e32 v9, v1
	v_lshl_add_u64 v[6:7], v[6:7], 0, v[8:9]
	s_waitcnt lgkmcnt(0)
	global_store_dwordx4 v[6:7], v[2:5], off sc1
	s_branch .LBB0_762

.LBB0_891:
	v_lshl_add_u64 v[70:71], v[144:145], 2, v[70:71]
	s_waitcnt lgkmcnt(0)
	global_store_dwordx4 v[70:71], v[66:69], off sc1

.LBB0_917:
	v_lshl_add_u64 v[70:71], v[144:145], 2, v[70:71]
	s_waitcnt lgkmcnt(0)
	global_store_dwordx4 v[70:71], v[66:69], off sc1
	s_branch .LBB0_885

.LBB0_953:
	v_add_u32_e32 v87, s26, v131
	v_ashrrev_i32_e32 v0, 6, v87
	v_mad_u64_u32 v[66:67], s[18:19], v0, s33, v[130:131]
	ds_read_b128 v[66:69], v66
	v_add_u32_e32 v70, s50, v0
	v_mad_i64_i32 v[88:89], s[18:19], v70, s96, v[132:133]
	s_movk_i32 s18, 0x3fff
	v_ashrrev_i32_e32 v71, 31, v70
	s_waitcnt lgkmcnt(0)
	v_cvt_pk_bf16_f32 v72, v66, v67
	v_cvt_pk_bf16_f32 v73, v68, v69
	v_cmp_lt_i32_e32 vcc, s18, v70
	global_store_dwordx2 v[88:89], v[72:73], off
	s_and_saveexec_b64 s[18:19], vcc
	s_xor_b64 s[18:19], exec, s[18:19]
	s_cbranch_execz .LBB0_957
	s_movk_i32 s24, 0x4080
	v_cmp_gt_u32_e32 vcc, s24, v70
	s_and_saveexec_b64 s[24:25], vcc
	s_cbranch_execz .LBB0_956
	v_readlane_b32 s52, v254, 7
	v_readlane_b32 s53, v254, 8
	s_load_dwordx2 s[52:53], s[52:53], 0x100
	v_add_u32_e32 v71, 0xffffc000, v70
	v_lshlrev_b32_e32 v0, 9, v71
	s_mov_b32 s27, 0x168f0000
	s_waitcnt lgkmcnt(0)
	s_add_u32 s52, s52, s8
	s_addc_u32 s53, s53, s9
	v_lshl_add_u64 v[88:89], v[0:1], 2, s[52:53]
	v_lshl_add_u64 v[88:89], v[134:135], 2, v[88:89]
	v_add_co_u32_e32 v88, vcc, s27, v88
	v_lshrrev_b32_e32 v0, 4, v71
	s_nop 0
	v_addc_co_u32_e32 v89, vcc, 0, v89, vcc
	s_movk_i32 s27, 0x840
	global_store_dwordx4 v[88:89], v[66:69], off sc1
	s_nop 1
	v_mad_u64_u32 v[66:67], s[52:53], v0, s27, 0
	v_and_or_b32 v66, v70, 15, v66
	v_lshlrev_b64 v[66:67], 10, v[66:67]
	v_lshl_add_u64 v[66:67], v[136:137], 0, v[66:67]
	v_add_co_u32_e32 v66, vcc, 0x1ff000, v66
	s_nop 1
	v_addc_co_u32_e32 v67, vcc, 0, v67, vcc
	global_store_dwordx2 v[66:67], v[72:73], off offset:1024

.LBB0_957:
	s_andn2_saveexec_b64 s[18:19], s[18:19]
	s_cbranch_execz .LBB0_959
	v_readlane_b32 s24, v254, 7
	v_readlane_b32 s25, v254, 8
	s_load_dwordx2 s[24:25], s[24:25], 0x100
	v_lshlrev_b64 v[70:71], 11, v[70:71]
	s_waitcnt lgkmcnt(0)
	s_add_u32 s24, s24, s4
	s_addc_u32 s25, s25, s5
	v_lshl_add_u64 v[70:71], s[24:25], 0, v[70:71]
	v_lshl_add_u64 v[70:71], v[134:135], 2, v[70:71]
	v_add_co_u32_e32 v70, vcc, 0x6880000, v70
	s_nop 1
	v_addc_co_u32_e32 v71, vcc, 0, v71, vcc
	global_store_dwordx4 v[70:71], v[66:69], off sc1
.LBB0_959:
	s_or_b64 exec, exec, s[18:19]
	v_add_u32_e32 v0, 0x200, v87
	v_ashrrev_i32_e32 v0, 6, v0
	v_mad_u64_u32 v[66:67], s[18:19], v0, s33, v[130:131]
	ds_read_b128 v[66:69], v66
	v_add_u32_e32 v70, s50, v0
	v_mad_i64_i32 v[88:89], s[18:19], v70, s96, v[132:133]
	s_movk_i32 s18, 0x3fff
	v_ashrrev_i32_e32 v71, 31, v70
	s_waitcnt lgkmcnt(0)
	v_cvt_pk_bf16_f32 v72, v66, v67
	v_cvt_pk_bf16_f32 v73, v68, v69
	v_cmp_lt_i32_e32 vcc, s18, v70
	global_store_dwordx2 v[88:89], v[72:73], off
	s_and_saveexec_b64 s[18:19], vcc
	s_xor_b64 s[18:19], exec, s[18:19]
	s_cbranch_execz .LBB0_963
	s_movk_i32 s24, 0x4080
	v_cmp_gt_u32_e32 vcc, s24, v70
	s_and_saveexec_b64 s[24:25], vcc
	s_cbranch_execz .LBB0_962
	v_readlane_b32 s52, v254, 7
	v_readlane_b32 s53, v254, 8
	s_load_dwordx2 s[52:53], s[52:53], 0x100
	v_add_u32_e32 v71, 0xffffc000, v70
	v_lshlrev_b32_e32 v0, 9, v71
	s_mov_b32 s27, 0x168f0000
	s_waitcnt lgkmcnt(0)
	s_add_u32 s52, s52, s8
	s_addc_u32 s53, s53, s9
	v_lshl_add_u64 v[88:89], v[0:1], 2, s[52:53]
	v_lshl_add_u64 v[88:89], v[134:135], 2, v[88:89]
	v_add_co_u32_e32 v88, vcc, s27, v88
	v_lshrrev_b32_e32 v0, 4, v71
	s_nop 0
	v_addc_co_u32_e32 v89, vcc, 0, v89, vcc
	s_movk_i32 s27, 0x840
	global_store_dwordx4 v[88:89], v[66:69], off sc1
	s_nop 1
	v_mad_u64_u32 v[66:67], s[52:53], v0, s27, 0
	v_and_or_b32 v66, v70, 15, v66
	v_lshlrev_b64 v[66:67], 10, v[66:67]
	v_lshl_add_u64 v[66:67], v[136:137], 0, v[66:67]
	v_add_co_u32_e32 v66, vcc, 0x1ff000, v66
	s_nop 1
	v_addc_co_u32_e32 v67, vcc, 0, v67, vcc
	global_store_dwordx2 v[66:67], v[72:73], off offset:1024

.LBB0_965:
	s_or_b64 exec, exec, s[18:19]
	v_add_u32_e32 v0, 0x400, v87
	v_ashrrev_i32_e32 v0, 6, v0
	v_mad_u64_u32 v[66:67], s[18:19], v0, s33, v[130:131]
	ds_read_b128 v[66:69], v66
	v_add_u32_e32 v70, s50, v0
	v_mad_i64_i32 v[88:89], s[18:19], v70, s96, v[132:133]
	s_movk_i32 s18, 0x3fff
	v_ashrrev_i32_e32 v71, 31, v70
	s_waitcnt lgkmcnt(0)
	v_cvt_pk_bf16_f32 v72, v66, v67
	v_cvt_pk_bf16_f32 v73, v68, v69
	v_cmp_lt_i32_e32 vcc, s18, v70
	global_store_dwordx2 v[88:89], v[72:73], off
	s_and_saveexec_b64 s[18:19], vcc
	s_xor_b64 s[18:19], exec, s[18:19]
	s_cbranch_execz .LBB0_969
	s_movk_i32 s24, 0x4080
	v_cmp_gt_u32_e32 vcc, s24, v70
	s_and_saveexec_b64 s[24:25], vcc
	s_cbranch_execz .LBB0_968
	v_readlane_b32 s52, v254, 7
	v_readlane_b32 s53, v254, 8
	s_load_dwordx2 s[52:53], s[52:53], 0x100
	v_add_u32_e32 v71, 0xffffc000, v70
	v_lshlrev_b32_e32 v0, 9, v71
	s_mov_b32 s27, 0x168f0000
	s_waitcnt lgkmcnt(0)
	s_add_u32 s52, s52, s8
	s_addc_u32 s53, s53, s9
	v_lshl_add_u64 v[88:89], v[0:1], 2, s[52:53]
	v_lshl_add_u64 v[88:89], v[134:135], 2, v[88:89]
	v_add_co_u32_e32 v88, vcc, s27, v88
	v_lshrrev_b32_e32 v0, 4, v71
	s_nop 0
	v_addc_co_u32_e32 v89, vcc, 0, v89, vcc
	s_movk_i32 s27, 0x840
	global_store_dwordx4 v[88:89], v[66:69], off sc1
	s_nop 1
	v_mad_u64_u32 v[66:67], s[52:53], v0, s27, 0
	v_and_or_b32 v66, v70, 15, v66
	v_lshlrev_b64 v[66:67], 10, v[66:67]
	v_lshl_add_u64 v[66:67], v[136:137], 0, v[66:67]
	v_add_co_u32_e32 v66, vcc, 0x1ff000, v66
	s_nop 1
	v_addc_co_u32_e32 v67, vcc, 0, v67, vcc
	global_store_dwordx2 v[66:67], v[72:73], off offset:1024

.LBB0_971:
	s_or_b64 exec, exec, s[18:19]
	v_add_u32_e32 v0, 0x600, v87
	v_ashrrev_i32_e32 v0, 6, v0
	v_mad_u64_u32 v[66:67], s[18:19], v0, s33, v[130:131]
	ds_read_b128 v[66:69], v66
	v_add_u32_e32 v70, s50, v0
	v_mad_i64_i32 v[88:89], s[18:19], v70, s96, v[132:133]
	s_movk_i32 s18, 0x3fff
	v_ashrrev_i32_e32 v71, 31, v70
	s_waitcnt lgkmcnt(0)
	v_cvt_pk_bf16_f32 v72, v66, v67
	v_cvt_pk_bf16_f32 v73, v68, v69
	v_cmp_lt_i32_e32 vcc, s18, v70
	global_store_dwordx2 v[88:89], v[72:73], off
	s_and_saveexec_b64 s[18:19], vcc
	s_xor_b64 s[18:19], exec, s[18:19]
	s_cbranch_execz .LBB0_975
	s_movk_i32 s24, 0x4080
	v_cmp_gt_u32_e32 vcc, s24, v70
	s_and_saveexec_b64 s[24:25], vcc
	s_cbranch_execz .LBB0_974
	v_readlane_b32 s52, v254, 7
	v_readlane_b32 s53, v254, 8
	s_load_dwordx2 s[52:53], s[52:53], 0x100
	v_add_u32_e32 v71, 0xffffc000, v70
	v_lshlrev_b32_e32 v0, 9, v71
	s_mov_b32 s27, 0x168f0000
	s_waitcnt lgkmcnt(0)
	s_add_u32 s52, s52, s8
	s_addc_u32 s53, s53, s9
	v_lshl_add_u64 v[88:89], v[0:1], 2, s[52:53]
	v_lshl_add_u64 v[88:89], v[134:135], 2, v[88:89]
	v_add_co_u32_e32 v88, vcc, s27, v88
	v_lshrrev_b32_e32 v0, 4, v71
	s_nop 0
	v_addc_co_u32_e32 v89, vcc, 0, v89, vcc
	s_movk_i32 s27, 0x840
	global_store_dwordx4 v[88:89], v[66:69], off sc1
	s_nop 1
	v_mad_u64_u32 v[66:67], s[52:53], v0, s27, 0
	v_and_or_b32 v66, v70, 15, v66
	v_lshlrev_b64 v[66:67], 10, v[66:67]
	v_lshl_add_u64 v[66:67], v[136:137], 0, v[66:67]
	v_add_co_u32_e32 v66, vcc, 0x1ff000, v66
	s_nop 1
	v_addc_co_u32_e32 v67, vcc, 0, v67, vcc
	global_store_dwordx2 v[66:67], v[72:73], off offset:1024

.LBB0_976:
	v_readlane_b32 s24, v254, 7
	v_readlane_b32 s25, v254, 8
	s_load_dwordx2 s[24:25], s[24:25], 0x100
	v_lshlrev_b64 v[70:71], 11, v[70:71]
	s_waitcnt lgkmcnt(0)
	s_add_u32 s24, s24, s4
	s_addc_u32 s25, s25, s5
	v_lshl_add_u64 v[70:71], s[24:25], 0, v[70:71]
	v_lshl_add_u64 v[70:71], v[134:135], 2, v[70:71]
	v_add_co_u32_e32 v70, vcc, 0x6880000, v70
	s_nop 1
	v_addc_co_u32_e32 v71, vcc, 0, v71, vcc
	global_store_dwordx4 v[70:71], v[66:69], off sc1
	s_branch .LBB0_952

.LBB0_1000:
	v_lshl_add_u64 v[6:7], v[144:145], 2, v[6:7]
	s_waitcnt lgkmcnt(0)
	global_store_dwordx4 v[6:7], v[2:5], off sc1

.LBB0_1026:
	v_lshl_add_u64 v[6:7], v[144:145], 2, v[6:7]
	s_waitcnt lgkmcnt(0)
	global_store_dwordx4 v[6:7], v[2:5], off sc1
	s_branch .LBB0_994

.LBB0_1062:
	v_add_u32_e32 v10, s18, v131
	v_ashrrev_i32_e32 v0, 6, v10
	v_mad_u64_u32 v[2:3], s[12:13], v0, s33, v[130:131]
	ds_read_b128 v[2:5], v2
	v_add_u32_e32 v6, s50, v0
	v_mad_i64_i32 v[12:13], s[12:13], v6, s96, v[132:133]
	s_movk_i32 s12, 0x3fff
	v_ashrrev_i32_e32 v7, 31, v6
	s_waitcnt lgkmcnt(0)
	v_cvt_pk_bf16_f32 v8, v2, v3
	v_cvt_pk_bf16_f32 v9, v4, v5
	v_cmp_lt_i32_e32 vcc, s12, v6
	global_store_dwordx2 v[12:13], v[8:9], off
	s_and_saveexec_b64 s[12:13], vcc
	s_xor_b64 s[12:13], exec, s[12:13]
	s_cbranch_execz .LBB0_1066
	s_movk_i32 s16, 0x4080
	v_cmp_gt_u32_e32 vcc, s16, v6
	s_and_saveexec_b64 s[16:17], vcc
	s_cbranch_execz .LBB0_1065
	v_readlane_b32 s24, v254, 7
	v_readlane_b32 s25, v254, 8
	s_load_dwordx2 s[24:25], s[24:25], 0x100
	v_add_u32_e32 v7, 0xffffc000, v6
	v_lshlrev_b32_e32 v0, 9, v7
	s_mov_b32 s19, 0x168f0000
	s_waitcnt lgkmcnt(0)
	s_add_u32 s24, s24, s8
	s_addc_u32 s25, s25, s9
	v_lshl_add_u64 v[12:13], v[0:1], 2, s[24:25]
	v_lshl_add_u64 v[12:13], v[134:135], 2, v[12:13]
	v_add_co_u32_e32 v12, vcc, s19, v12
	v_lshrrev_b32_e32 v0, 4, v7
	s_nop 0
	v_addc_co_u32_e32 v13, vcc, 0, v13, vcc
	s_movk_i32 s19, 0x840
	global_store_dwordx4 v[12:13], v[2:5], off sc1
	s_nop 1
	v_mad_u64_u32 v[2:3], s[24:25], v0, s19, 0
	v_and_or_b32 v2, v6, 15, v2
	v_lshlrev_b64 v[2:3], 10, v[2:3]
	v_lshl_add_u64 v[2:3], v[136:137], 0, v[2:3]
	v_add_co_u32_e32 v2, vcc, 0x1ff000, v2
	s_nop 1
	v_addc_co_u32_e32 v3, vcc, 0, v3, vcc
	global_store_dwordx2 v[2:3], v[8:9], off offset:1024

.LBB0_1066:
	s_andn2_saveexec_b64 s[12:13], s[12:13]
	s_cbranch_execz .LBB0_1068
	v_readlane_b32 s16, v254, 7
	v_readlane_b32 s17, v254, 8
	s_load_dwordx2 s[16:17], s[16:17], 0x100
	v_lshlrev_b64 v[6:7], 11, v[6:7]
	s_waitcnt lgkmcnt(0)
	s_add_u32 s16, s16, s4
	s_addc_u32 s17, s17, s5
	v_lshl_add_u64 v[6:7], s[16:17], 0, v[6:7]
	v_lshl_add_u64 v[6:7], v[134:135], 2, v[6:7]
	v_add_co_u32_e32 v6, vcc, 0x6880000, v6
	s_nop 1
	v_addc_co_u32_e32 v7, vcc, 0, v7, vcc
	global_store_dwordx4 v[6:7], v[2:5], off sc1
.LBB0_1068:
	s_or_b64 exec, exec, s[12:13]
	v_add_u32_e32 v0, 0x200, v10
	v_ashrrev_i32_e32 v0, 6, v0
	v_mad_u64_u32 v[2:3], s[12:13], v0, s33, v[130:131]
	ds_read_b128 v[2:5], v2
	v_add_u32_e32 v6, s50, v0
	v_mad_i64_i32 v[12:13], s[12:13], v6, s96, v[132:133]
	s_movk_i32 s12, 0x3fff
	v_ashrrev_i32_e32 v7, 31, v6
	s_waitcnt lgkmcnt(0)
	v_cvt_pk_bf16_f32 v8, v2, v3
	v_cvt_pk_bf16_f32 v9, v4, v5
	v_cmp_lt_i32_e32 vcc, s12, v6
	global_store_dwordx2 v[12:13], v[8:9], off
	s_and_saveexec_b64 s[12:13], vcc
	s_xor_b64 s[12:13], exec, s[12:13]
	s_cbranch_execz .LBB0_1072
	s_movk_i32 s16, 0x4080
	v_cmp_gt_u32_e32 vcc, s16, v6
	s_and_saveexec_b64 s[16:17], vcc
	s_cbranch_execz .LBB0_1071
	v_readlane_b32 s24, v254, 7
	v_readlane_b32 s25, v254, 8
	s_load_dwordx2 s[24:25], s[24:25], 0x100
	v_add_u32_e32 v7, 0xffffc000, v6
	v_lshlrev_b32_e32 v0, 9, v7
	s_mov_b32 s19, 0x168f0000
	s_waitcnt lgkmcnt(0)
	s_add_u32 s24, s24, s8
	s_addc_u32 s25, s25, s9
	v_lshl_add_u64 v[12:13], v[0:1], 2, s[24:25]
	v_lshl_add_u64 v[12:13], v[134:135], 2, v[12:13]
	v_add_co_u32_e32 v12, vcc, s19, v12
	v_lshrrev_b32_e32 v0, 4, v7
	s_nop 0
	v_addc_co_u32_e32 v13, vcc, 0, v13, vcc
	s_movk_i32 s19, 0x840
	global_store_dwordx4 v[12:13], v[2:5], off sc1
	s_nop 1
	v_mad_u64_u32 v[2:3], s[24:25], v0, s19, 0
	v_and_or_b32 v2, v6, 15, v2
	v_lshlrev_b64 v[2:3], 10, v[2:3]
	v_lshl_add_u64 v[2:3], v[136:137], 0, v[2:3]
	v_add_co_u32_e32 v2, vcc, 0x1ff000, v2
	s_nop 1
	v_addc_co_u32_e32 v3, vcc, 0, v3, vcc
	global_store_dwordx2 v[2:3], v[8:9], off offset:1024

.LBB0_1074:
	s_or_b64 exec, exec, s[12:13]
	v_add_u32_e32 v0, 0x400, v10
	v_ashrrev_i32_e32 v0, 6, v0
	v_mad_u64_u32 v[2:3], s[12:13], v0, s33, v[130:131]
	ds_read_b128 v[2:5], v2
	v_add_u32_e32 v6, s50, v0
	v_mad_i64_i32 v[12:13], s[12:13], v6, s96, v[132:133]
	s_movk_i32 s12, 0x3fff
	v_ashrrev_i32_e32 v7, 31, v6
	s_waitcnt lgkmcnt(0)
	v_cvt_pk_bf16_f32 v8, v2, v3
	v_cvt_pk_bf16_f32 v9, v4, v5
	v_cmp_lt_i32_e32 vcc, s12, v6
	global_store_dwordx2 v[12:13], v[8:9], off
	s_and_saveexec_b64 s[12:13], vcc
	s_xor_b64 s[12:13], exec, s[12:13]
	s_cbranch_execz .LBB0_1078
	s_movk_i32 s16, 0x4080
	v_cmp_gt_u32_e32 vcc, s16, v6
	s_and_saveexec_b64 s[16:17], vcc
	s_cbranch_execz .LBB0_1077
	v_readlane_b32 s24, v254, 7
	v_readlane_b32 s25, v254, 8
	s_load_dwordx2 s[24:25], s[24:25], 0x100
	v_add_u32_e32 v7, 0xffffc000, v6
	v_lshlrev_b32_e32 v0, 9, v7
	s_mov_b32 s19, 0x168f0000
	s_waitcnt lgkmcnt(0)
	s_add_u32 s24, s24, s8
	s_addc_u32 s25, s25, s9
	v_lshl_add_u64 v[12:13], v[0:1], 2, s[24:25]
	v_lshl_add_u64 v[12:13], v[134:135], 2, v[12:13]
	v_add_co_u32_e32 v12, vcc, s19, v12
	v_lshrrev_b32_e32 v0, 4, v7
	s_nop 0
	v_addc_co_u32_e32 v13, vcc, 0, v13, vcc
	s_movk_i32 s19, 0x840
	global_store_dwordx4 v[12:13], v[2:5], off sc1
	s_nop 1
	v_mad_u64_u32 v[2:3], s[24:25], v0, s19, 0
	v_and_or_b32 v2, v6, 15, v2
	v_lshlrev_b64 v[2:3], 10, v[2:3]
	v_lshl_add_u64 v[2:3], v[136:137], 0, v[2:3]
	v_add_co_u32_e32 v2, vcc, 0x1ff000, v2
	s_nop 1
	v_addc_co_u32_e32 v3, vcc, 0, v3, vcc
	global_store_dwordx2 v[2:3], v[8:9], off offset:1024

.LBB0_1080:
	s_or_b64 exec, exec, s[12:13]
	v_add_u32_e32 v0, 0x600, v10
	v_ashrrev_i32_e32 v0, 6, v0
	v_mad_u64_u32 v[2:3], s[12:13], v0, s33, v[130:131]
	ds_read_b128 v[2:5], v2
	v_add_u32_e32 v6, s50, v0
	v_mad_i64_i32 v[10:11], s[12:13], v6, s96, v[132:133]
	s_movk_i32 s12, 0x3fff
	v_ashrrev_i32_e32 v7, 31, v6
	s_waitcnt lgkmcnt(0)
	v_cvt_pk_bf16_f32 v8, v2, v3
	v_cvt_pk_bf16_f32 v9, v4, v5
	v_cmp_lt_i32_e32 vcc, s12, v6
	global_store_dwordx2 v[10:11], v[8:9], off
	s_and_saveexec_b64 s[12:13], vcc
	s_xor_b64 s[12:13], exec, s[12:13]
	s_cbranch_execz .LBB0_1084
	s_movk_i32 s16, 0x4080
	v_cmp_gt_u32_e32 vcc, s16, v6
	s_and_saveexec_b64 s[16:17], vcc
	s_cbranch_execz .LBB0_1083
	v_readlane_b32 s24, v254, 7
	v_readlane_b32 s25, v254, 8
	s_load_dwordx2 s[24:25], s[24:25], 0x100
	v_add_u32_e32 v7, 0xffffc000, v6
	v_lshlrev_b32_e32 v0, 9, v7
	s_mov_b32 s19, 0x168f0000
	s_waitcnt lgkmcnt(0)
	s_add_u32 s24, s24, s8
	s_addc_u32 s25, s25, s9
	v_lshl_add_u64 v[10:11], v[0:1], 2, s[24:25]
	v_lshl_add_u64 v[10:11], v[134:135], 2, v[10:11]
	v_add_co_u32_e32 v10, vcc, s19, v10
	v_lshrrev_b32_e32 v0, 4, v7
	s_nop 0
	v_addc_co_u32_e32 v11, vcc, 0, v11, vcc
	s_movk_i32 s19, 0x840
	global_store_dwordx4 v[10:11], v[2:5], off sc1
	s_nop 1
	v_mad_u64_u32 v[2:3], s[24:25], v0, s19, 0
	v_and_or_b32 v2, v6, 15, v2
	v_lshlrev_b64 v[2:3], 10, v[2:3]
	v_lshl_add_u64 v[2:3], v[136:137], 0, v[2:3]
	v_add_co_u32_e32 v2, vcc, 0x1ff000, v2
	s_nop 1
	v_addc_co_u32_e32 v3, vcc, 0, v3, vcc
	global_store_dwordx2 v[2:3], v[8:9], off offset:1024

.LBB0_1085:
	v_readlane_b32 s16, v254, 7
	v_readlane_b32 s17, v254, 8
	s_load_dwordx2 s[16:17], s[16:17], 0x100
	v_lshlrev_b64 v[6:7], 11, v[6:7]
	s_waitcnt lgkmcnt(0)
	s_add_u32 s16, s16, s4
	s_addc_u32 s17, s17, s5
	v_lshl_add_u64 v[6:7], s[16:17], 0, v[6:7]
	v_lshl_add_u64 v[6:7], v[134:135], 2, v[6:7]
	v_add_co_u32_e32 v6, vcc, 0x6880000, v6
	s_nop 1
	v_addc_co_u32_e32 v7, vcc, 0, v7, vcc
	global_store_dwordx4 v[6:7], v[2:5], off sc1
	s_branch .LBB0_1061

.LBB0_1271:
	v_ashrrev_i32_e32 v3, 31, v2
	v_lshlrev_b64 v[14:15], 12, v[2:3]
	v_lshl_add_u64 v[34:35], v[6:7], 0, v[14:15]
	global_load_dwordx4 v[14:17], v[34:35], off
	global_load_dwordx4 v[18:21], v[34:35], off offset:1024
	global_load_dwordx4 v[22:25], v[34:35], off offset:2048
	global_load_dwordx4 v[26:29], v[34:35], off offset:3072
	global_load_dwordx4 v[30:33], v[4:5], off
	v_add_u32_e32 v2, s0, v2
	s_waitcnt vmcnt(4)
	v_mov_b32_e32 v38, v15
	s_waitcnt vmcnt(3)
	v_mov_b32_e32 v39, v19
	v_mov_b32_e32 v36, v14
	v_mov_b32_e32 v37, v18
	s_waitcnt vmcnt(2)
	v_mov_b32_e32 v46, v23
	s_waitcnt vmcnt(1)
	v_mov_b32_e32 v47, v27
	v_pk_mul_f32 v[38:39], v[38:39], v[38:39]
	v_mov_b32_e32 v40, v16
	v_mov_b32_e32 v41, v20
	v_mov_b32_e32 v44, v22
	v_mov_b32_e32 v45, v26
	v_pk_mul_f32 v[46:47], v[46:47], v[46:47]
	v_pk_fma_f32 v[36:37], v[36:37], v[36:37], v[38:39]
	v_mov_b32_e32 v42, v17
	v_mov_b32_e32 v43, v21
	v_mov_b32_e32 v48, v24
	v_mov_b32_e32 v49, v28
	v_pk_fma_f32 v[38:39], v[44:45], v[44:45], v[46:47]
	v_pk_fma_f32 v[36:37], v[40:41], v[40:41], v[36:37]
	v_mov_b32_e32 v50, v25
	v_mov_b32_e32 v51, v29
	v_pk_fma_f32 v[38:39], v[48:49], v[48:49], v[38:39]
	v_pk_fma_f32 v[36:37], v[42:43], v[42:43], v[36:37]
	v_pk_fma_f32 v[38:39], v[50:51], v[50:51], v[38:39]
	v_add_f32_e32 v0, v36, v37
	v_add_f32_e32 v0, v0, v38
	v_add_f32_e32 v0, v0, v39
	ds_bpermute_b32 v3, v8, v0
	s_waitcnt lgkmcnt(0)
	v_add_f32_e32 v0, v0, v3
	ds_bpermute_b32 v3, v9, v0
	s_waitcnt lgkmcnt(0)
	v_add_f32_e32 v0, v0, v3
	ds_bpermute_b32 v3, v10, v0
	s_waitcnt lgkmcnt(0)
	v_add_f32_e32 v0, v0, v3
	ds_bpermute_b32 v3, v11, v0
	s_waitcnt lgkmcnt(0)
	v_add_f32_e32 v0, v0, v3
	ds_bpermute_b32 v3, v12, v0
	s_waitcnt lgkmcnt(0)
	v_add_f32_e32 v0, v0, v3
	ds_bpermute_b32 v3, v13, v0
	s_waitcnt lgkmcnt(0)
	v_add_f32_e32 v0, v0, v3
	v_fmamk_f32 v0, v0, 0x3a800000, v170
	v_mul_f32_e32 v3, 0x4b800000, v0
	v_cmp_gt_f32_e32 vcc, s12, v0
	s_nop 1
	v_cndmask_b32_e32 v0, v0, v3, vcc
	v_rsq_f32_e32 v0, v0
	s_nop 0
	v_mul_f32_e32 v3, 0x45800000, v0
	v_cndmask_b32_e32 v0, v0, v3, vcc
	v_pk_mul_f32 v[14:15], v[14:15], v[0:1] op_sel_hi:[1,0]
	v_pk_mul_f32 v[16:17], v[16:17], v[0:1] op_sel_hi:[1,0]
	s_waitcnt vmcnt(0)
	v_pk_mul_f32 v[14:15], v[30:31], v[14:15]
	v_pk_mul_f32 v[16:17], v[32:33], v[16:17]
	global_store_dwordx4 v[34:35], v[14:17], off sc1
	global_load_dwordx4 v[14:17], v[4:5], off offset:1024
	v_pk_mul_f32 v[18:19], v[18:19], v[0:1] op_sel_hi:[1,0]
	v_pk_mul_f32 v[20:21], v[20:21], v[0:1] op_sel_hi:[1,0]
	v_cmp_lt_i32_e32 vcc, s13, v2
	s_or_b64 s[6:7], vcc, s[6:7]
	s_waitcnt vmcnt(0)
	v_pk_mul_f32 v[14:15], v[14:15], v[18:19]
	v_pk_mul_f32 v[16:17], v[16:17], v[20:21]
	global_store_dwordx4 v[34:35], v[14:17], off offset:1024 sc1
	global_load_dwordx4 v[14:17], v[4:5], off offset:2048
	v_pk_mul_f32 v[18:19], v[22:23], v[0:1] op_sel_hi:[1,0]
	v_pk_mul_f32 v[20:21], v[24:25], v[0:1] op_sel_hi:[1,0]
	s_waitcnt vmcnt(0)
	v_pk_mul_f32 v[14:15], v[18:19], v[14:15]
	v_pk_mul_f32 v[16:17], v[20:21], v[16:17]
	global_store_dwordx4 v[34:35], v[14:17], off offset:2048 sc1
	global_load_dwordx4 v[14:17], v[4:5], off offset:3072
	v_pk_mul_f32 v[18:19], v[26:27], v[0:1] op_sel_hi:[1,0]
	v_pk_mul_f32 v[20:21], v[28:29], v[0:1] op_sel_hi:[1,0]
	s_waitcnt vmcnt(0)
	v_pk_mul_f32 v[14:15], v[18:19], v[14:15]
	v_pk_mul_f32 v[16:17], v[20:21], v[16:17]
	global_store_dwordx4 v[34:35], v[14:17], off offset:3072 sc1
	s_andn2_b64 exec, exec, s[6:7]
	s_cbranch_execnz .LBB0_1271
